# lever7: K-loop LDS-DMA loads in saddr form (SGPR base + 32-bit lane offset, +128 steps as inst offset with m0 compensated) and one precomputed ds_read base: 20 VALU adds per K-iteration removed from t
# speedup vs baseline: 1.0122x; 1.0122x over previous
.LBB0_392:
	s_and_b32 s8, s6, 3
	s_lshl_b32 s81, s7, 6
	s_lshl_b32 s3, s7, 13
	s_lshl_b32 s6, s8, 12
	s_cmpk_gt_u32 s61, 0xff
	s_cselect_b64 s[38:39], -1, 0
	s_add_i32 s4, s50, -11
	s_cmp_gt_u32 s4, 2
	s_cselect_b64 s[40:41], -1, 0
	s_add_i32 m0, s69, 0x18000
	v_lshl_add_u64 v[6:7], v[6:7], 0, s[62:63]
	s_waitcnt vmcnt(2)
	s_barrier
	global_load_lds_dwordx4 v[6:7], off
	v_lshl_add_u64 v[4:5], v[4:5], 0, s[62:63]
	s_add_i32 m0, s69, 0x1a000
	s_add_i32 s96, s69, 0x8000
	s_add_i32 s36, s69, 0xa000
	global_load_lds_dwordx4 v[4:5], off
	v_lshl_add_u64 v[0:1], v[0:1], 0, s[62:63]
	s_mov_b32 m0, s96
	s_add_u32 s4, s12, 0x10080
	global_load_lds_dwordx4 v[0:1], off
	v_lshl_add_u64 v[0:1], v[2:3], 0, s[62:63]
	s_mov_b32 m0, s36
	s_addc_u32 s5, s13, 0
	global_load_lds_dwordx4 v[0:1], off
	s_add_i32 m0, s69, 0x1c000
	v_lshl_add_u64 v[0:1], s[4:5], 0, v[156:157]
	global_load_lds_dwordx4 v[0:1], off
	v_lshl_add_u64 v[0:1], s[4:5], 0, v[160:161]
	s_add_i32 m0, s69, 0x1e000
	v_bfe_u32 v2, v8, 4, 2
	global_load_lds_dwordx4 v[0:1], off
	s_cmpk_lt_u32 s16, 0x100
	v_and_b32_e32 v163, 15, v8
	v_lshlrev_b32_e32 v1, 4, v2
	v_lshlrev_b32_e32 v4, 2, v8
	s_cselect_b64 s[42:43], -1, 0
	s_or_b32 s9, s81, 48
	v_or_b32_e32 v0, s81, v163
	v_lshl_or_b32 v3, v163, 6, v1
	v_and_b32_e32 v162, 32, v4
	v_writelane_b32 v252, s9, 38
	s_and_b32 s9, s16, 0xffffff00
	v_bitop3_b32 v4, v3, s3, v162 bitop3:0xde
	v_bitop3_b32 v221, v3, s6, v162 bitop3:0xde
	v_add_u32_e32 v253, 0x10000, v221
	s_lshl_b32 s10, s8, 6
	v_lshlrev_b32_e32 v3, 4, v0
	v_or_b32_e32 v0, s9, v163
	v_or3_b32 v0, v0, v1, s10
	v_readlane_b32 s11, v252, 2
	v_ashrrev_i32_e32 v1, 31, v0
	v_lshlrev_b64 v[164:165], 4, v[0:1]
	v_add_u32_e32 v223, s11, v3
	v_readlane_b32 s11, v252, 3
	v_lshlrev_b32_e32 v1, 14, v9
	v_and_b32_e32 v1, 0xffff8000, v1
	v_add_u32_e32 v224, s11, v3
	v_readlane_b32 s11, v252, 4
	v_cmp_eq_u32_e64 s[44:45], 0, v2
	v_lshl_or_b32 v230, v2, 3, s10
	v_add_u32_e32 v225, s11, v3
	v_readlane_b32 s11, v252, 5
	v_lshl_add_u32 v1, v10, 11, v1
	v_and_b32_e32 v2, 1, v9
	v_add_u32_e32 v226, s11, v3
	v_readlane_b32 s11, v252, 6
	v_lshl_or_b32 v1, v2, 6, v1
	s_mov_b32 s3, s91
	v_add_u32_e32 v227, s11, v3
	v_readlane_b32 s11, v252, 7
	s_mul_i32 s4, s61, 0x40800
	s_mov_b32 s5, s91
	v_add_u32_e32 v228, s11, v3
	v_readlane_b32 s11, v252, 8
	v_lshl_add_u32 v166, v11, 1, v1
	v_lshlrev_b32_e32 v1, 14, v12
	s_movk_i32 s9, 0x100
	v_add_u32_e32 v229, s11, v3
	v_readlane_b32 s11, v252, 9
	v_and_b32_e32 v1, 0xffff8000, v1
	s_lshl_b64 s[48:49], s[2:3], 2
	s_lshl_b64 s[2:3], s[4:5], 2
	s_waitcnt vmcnt(6)
	s_lshl_b32 s8, s8, 2
	v_cmp_gt_i32_e64 s[92:93], s9, v0
	v_lshlrev_b32_e32 v5, 4, v0
	v_add_u32_e32 v0, s11, v3
	v_lshl_add_u32 v1, v13, 11, v1
	v_and_b32_e32 v2, 1, v12
	v_writelane_b32 v252, s2, 40
	s_mul_i32 s90, s61, 0x24000
	s_or_b32 s17, s81, 32
	v_lshl_or_b32 v1, v2, 6, v1
	v_add_u32_e32 v232, s8, v0
	v_writelane_b32 v252, s3, 41
	v_add_u32_e32 v0, 0, v5
	s_mov_b32 s51, s50
	v_cmp_gt_u32_e64 s[6:7], 8, v163
	v_and_b32_e32 v222, 7, v8
	s_mov_b32 s37, 0
	s_or_b32 s74, s81, 16
	s_ashr_i32 s9, s25, 31
	s_ashr_i32 s50, s80, 31
	v_mov_b32_e32 v167, v97
	v_lshl_add_u32 v168, v14, 1, v1
	v_mov_b32_e32 v169, v97
	v_add_u32_e32 v231, 0, v4
	s_lshl_b64 s[46:47], s[90:91], 2
	s_mov_b32 s90, s17
	v_add_u32_e32 v233, 0x20000, v0
	v_writelane_b32 v252, s82, 36
	s_barrier
	s_nop 0
	v_writelane_b32 v252, s83, 37
	s_branch .LBB0_395

.LBB0_404:
	s_ashr_i32 s55, s54, 31
	s_lshl_b64 s[2:3], s[54:55], 19
	s_add_u32 s56, s60, s2
	s_addc_u32 s57, s65, s3
	s_and_b64 s[2:3], s[10:11], exec
	s_cselect_b32 s16, s57, s15
	s_cselect_b32 s17, s56, s14
	s_ashr_i32 s31, s30, 31
	s_lshl_b64 s[2:3], s[30:31], 19
	s_add_u32 s4, s66, s2
	s_addc_u32 s5, s68, s3
	s_and_b64 s[2:3], s[10:11], exec
	s_cselect_b32 s18, s5, s13
	s_cselect_b32 s19, s4, s12
	s_add_u32 s2, s14, 0x40080
	s_addc_u32 s3, s15, 0
	s_add_u32 s20, s12, 0x100
	s_addc_u32 s21, s13, 0
	s_mov_b32 s22, -2
	s_add_u32 s12, s2, 0xfffc0080
	s_addc_u32 s13, s3, -1
	s_add_i32 s23, 0, 0x10000
	s_cmp_eq_u32 s22, 12
	s_cselect_b32 s15, s16, s13
	s_cselect_b32 s14, s17, s12
	s_cselect_b32 s13, s18, s21
	s_cselect_b32 s12, s19, s20
	s_add_i32 s31, 0, 0x14000
	ds_read_b128 v[0:3], v253
	ds_read_b128 v[4:7], v253 offset:1024
	ds_read_b128 v[138:141], v253 offset:2048
	ds_read_b128 v[142:145], v253 offset:3072
	ds_read_b128 v[146:149], v253 offset:16384
	ds_read_b128 v[150:153], v253 offset:17408
	ds_read_b128 v[180:183], v253 offset:18432
	ds_read_b128 v[184:187], v253 offset:19456
	s_add_i32 m0, s69, 0xc000
	ds_read_b128 v[188:191], v231
	ds_read_b128 v[192:195], v231 offset:1024
	ds_read_b128 v[196:199], v231 offset:2048
	ds_read_b128 v[200:203], v231 offset:3072
	ds_read_b128 v[204:207], v231 offset:4096
	ds_read_b128 v[234:237], v231 offset:5120
	ds_read_b128 v[238:241], v231 offset:6144
	ds_read_b128 v[242:245], v231 offset:7168
	global_load_lds_dwordx4 v166, s[2:3]
	s_add_i32 m0, s69, 0xe000
	s_nop 0
	global_load_lds_dwordx4 v168, s[2:3]
	s_cmp_lg_u32 s100, 0
	s_cbranch_scc1 .Lpl_out_r1
	s_waitcnt vmcnt(8)
	s_branch .Lpl_out_j1

.Lpl_out_j1:
	s_waitcnt lgkmcnt(0)
	s_barrier
	s_setprio 1
	s_waitcnt lgkmcnt(0)
	v_mfma_f32_16x16x32_bf16 v[134:137], v[0:3], v[188:191], 0
	v_mfma_f32_16x16x32_bf16 v[130:133], v[138:141], v[188:191], 0
	v_mfma_f32_16x16x32_bf16 v[118:121], v[0:3], v[196:199], 0
	v_mfma_f32_16x16x32_bf16 v[114:117], v[138:141], v[196:199], 0
	v_mfma_f32_16x16x32_bf16 v[102:105], v[0:3], v[204:207], 0
	v_mfma_f32_16x16x32_bf16 v[98:101], v[138:141], v[204:207], 0
	v_mfma_f32_16x16x32_bf16 v[84:87], v[0:3], v[238:241], 0
	v_mfma_f32_16x16x32_bf16 v[80:83], v[138:141], v[238:241], 0
	v_mfma_f32_16x16x32_bf16 v[134:137], v[4:7], v[192:195], v[134:137]
	v_mfma_f32_16x16x32_bf16 v[130:133], v[142:145], v[192:195], v[130:133]
	v_mfma_f32_16x16x32_bf16 v[118:121], v[4:7], v[200:203], v[118:121]
	v_mfma_f32_16x16x32_bf16 v[114:117], v[142:145], v[200:203], v[114:117]
	v_mfma_f32_16x16x32_bf16 v[102:105], v[4:7], v[234:237], v[102:105]
	v_mfma_f32_16x16x32_bf16 v[98:101], v[142:145], v[234:237], v[98:101]
	v_mfma_f32_16x16x32_bf16 v[84:87], v[4:7], v[242:245], v[84:87]
	v_mfma_f32_16x16x32_bf16 v[80:83], v[142:145], v[242:245], v[80:83]
	s_setprio 0
	s_setprio 1
	v_mfma_f32_16x16x32_bf16 v[126:129], v[146:149], v[188:191], 0
	v_mfma_f32_16x16x32_bf16 v[122:125], v[180:183], v[188:191], 0
	v_mfma_f32_16x16x32_bf16 v[110:113], v[146:149], v[196:199], 0
	v_mfma_f32_16x16x32_bf16 v[106:109], v[180:183], v[196:199], 0
	v_mfma_f32_16x16x32_bf16 v[92:95], v[146:149], v[204:207], 0
	v_mfma_f32_16x16x32_bf16 v[88:91], v[180:183], v[204:207], 0
	v_mfma_f32_16x16x32_bf16 v[76:79], v[146:149], v[238:241], 0
	v_mfma_f32_16x16x32_bf16 v[72:75], v[180:183], v[238:241], 0
	v_mfma_f32_16x16x32_bf16 v[126:129], v[150:153], v[192:195], v[126:129]
	v_mfma_f32_16x16x32_bf16 v[122:125], v[184:187], v[192:195], v[122:125]
	v_mfma_f32_16x16x32_bf16 v[110:113], v[150:153], v[200:203], v[110:113]
	v_mfma_f32_16x16x32_bf16 v[106:109], v[184:187], v[200:203], v[106:109]
	v_mfma_f32_16x16x32_bf16 v[92:95], v[150:153], v[234:237], v[92:95]
	v_mfma_f32_16x16x32_bf16 v[88:91], v[184:187], v[234:237], v[88:91]
	v_mfma_f32_16x16x32_bf16 v[76:79], v[150:153], v[242:245], v[76:79]
	v_mfma_f32_16x16x32_bf16 v[72:75], v[184:187], v[242:245], v[72:75]
	s_setprio 0
	s_barrier
	s_add_i32 s23, s23, s58
	s_mov_b32 m0, s23
	ds_read_b128 v[188:191], v231 offset:16384
	ds_read_b128 v[192:195], v231 offset:17408
	ds_read_b128 v[196:199], v231 offset:18432
	ds_read_b128 v[200:203], v231 offset:19456
	ds_read_b128 v[204:207], v231 offset:20480
	ds_read_b128 v[234:237], v231 offset:21504
	ds_read_b128 v[238:241], v231 offset:22528
	ds_read_b128 v[242:245], v231 offset:23552
	global_load_lds_dwordx4 v156, s[12:13]
	s_add_i32 m0, s23, 0x2000
	s_add_u32 s26, s12, 0x10000
	s_addc_u32 s27, s13, 0
	s_add_i32 s23, s31, s58
	global_load_lds_dwordx4 v160, s[12:13]
	s_mov_b32 m0, s23
	s_nop 0
	global_load_lds_dwordx4 v156, s[26:27]
	s_add_i32 m0, s23, 0x2000
	s_nop 0
	global_load_lds_dwordx4 v160, s[26:27]
	s_mov_b64 s[26:27], s[14:15]
	s_mov_b32 m0, s69
	s_nop 0
	global_load_lds_dwordx4 v154, s[14:15]
	s_mov_b32 m0, s70
	s_nop 0
	global_load_lds_dwordx4 v158, s[14:15]
	s_cmp_lg_u32 s100, 0
	s_cbranch_scc1 .Lpl_out_r2
	s_waitcnt vmcnt(8)
	s_branch .Lpl_out_j2

.Lpl_out_j2:
	s_mov_b32 s100, 0
	s_waitcnt lgkmcnt(0)
	s_barrier
	s_setprio 1
	s_waitcnt lgkmcnt(0)
	v_mfma_f32_16x16x32_bf16 v[68:71], v[0:3], v[188:191], 0
	v_mfma_f32_16x16x32_bf16 v[64:67], v[138:141], v[188:191], 0
	v_mfma_f32_16x16x32_bf16 v[52:55], v[0:3], v[196:199], 0
	v_mfma_f32_16x16x32_bf16 v[48:51], v[138:141], v[196:199], 0
	v_mfma_f32_16x16x32_bf16 v[36:39], v[0:3], v[204:207], 0
	v_mfma_f32_16x16x32_bf16 v[32:35], v[138:141], v[204:207], 0
	v_mfma_f32_16x16x32_bf16 v[0:3], v[0:3], v[238:241], 0
	v_mfma_f32_16x16x32_bf16 v[68:71], v[4:7], v[192:195], v[68:71]
	v_mfma_f32_16x16x32_bf16 v[64:67], v[142:145], v[192:195], v[64:67]
	v_mfma_f32_16x16x32_bf16 v[52:55], v[4:7], v[200:203], v[52:55]
	v_mfma_f32_16x16x32_bf16 v[48:51], v[142:145], v[200:203], v[48:51]
	v_mfma_f32_16x16x32_bf16 v[36:39], v[4:7], v[234:237], v[36:39]
	v_mfma_f32_16x16x32_bf16 v[32:35], v[142:145], v[234:237], v[32:35]
	v_mfma_f32_16x16x32_bf16 v[0:3], v[4:7], v[242:245], v[0:3]
	v_mfma_f32_16x16x32_bf16 v[4:7], v[138:141], v[238:241], 0
	v_mfma_f32_16x16x32_bf16 v[4:7], v[142:145], v[242:245], v[4:7]
	s_setprio 0
	s_setprio 1
	v_mfma_f32_16x16x32_bf16 v[16:19], v[146:149], v[188:191], 0
	v_mfma_f32_16x16x32_bf16 v[60:63], v[150:153], v[192:195], v[16:19]
	v_mfma_f32_16x16x32_bf16 v[16:19], v[180:183], v[188:191], 0
	v_mfma_f32_16x16x32_bf16 v[56:59], v[184:187], v[192:195], v[16:19]
	v_mfma_f32_16x16x32_bf16 v[16:19], v[146:149], v[196:199], 0
	v_mfma_f32_16x16x32_bf16 v[44:47], v[150:153], v[200:203], v[16:19]
	v_mfma_f32_16x16x32_bf16 v[16:19], v[180:183], v[196:199], 0
	v_mfma_f32_16x16x32_bf16 v[40:43], v[184:187], v[200:203], v[16:19]
	v_mfma_f32_16x16x32_bf16 v[16:19], v[146:149], v[204:207], 0
	v_mfma_f32_16x16x32_bf16 v[28:31], v[150:153], v[234:237], v[16:19]
	v_mfma_f32_16x16x32_bf16 v[16:19], v[180:183], v[204:207], 0
	v_mfma_f32_16x16x32_bf16 v[12:15], v[146:149], v[238:241], 0
	v_mfma_f32_16x16x32_bf16 v[8:11], v[180:183], v[238:241], 0
	v_mfma_f32_16x16x32_bf16 v[24:27], v[184:187], v[234:237], v[16:19]
	v_mfma_f32_16x16x32_bf16 v[12:15], v[150:153], v[242:245], v[12:15]
	v_mfma_f32_16x16x32_bf16 v[8:11], v[184:187], v[242:245], v[8:11]
	s_setprio 0
	s_barrier
	s_add_i32 s23, 0, 0x1c000
	ds_read_b128 v[16:19], v253 offset:32768
	ds_read_b128 v[20:23], v253 offset:33792
	ds_read_b128 v[138:141], v253 offset:34816
	ds_read_b128 v[142:145], v253 offset:35840
	ds_read_b128 v[146:149], v253 offset:49152
	ds_read_b128 v[150:153], v253 offset:50176
	ds_read_b128 v[180:183], v253 offset:51200
	ds_read_b128 v[184:187], v253 offset:52224
	s_add_u32 s14, s14, 0x40000
	s_addc_u32 s15, s15, 0
	s_mov_b32 m0, s71
	ds_read_b128 v[188:191], v231 offset:32768
	ds_read_b128 v[192:195], v231 offset:33792
	ds_read_b128 v[196:199], v231 offset:34816
	ds_read_b128 v[200:203], v231 offset:35840
	ds_read_b128 v[204:207], v231 offset:36864
	ds_read_b128 v[234:237], v231 offset:37888
	ds_read_b128 v[238:241], v231 offset:38912
	ds_read_b128 v[242:245], v231 offset:39936
	global_load_lds_dwordx4 v154, s[14:15]
	s_mov_b32 m0, s76
	s_nop 0
	global_load_lds_dwordx4 v158, s[14:15]
	s_waitcnt vmcnt(8)
	s_waitcnt lgkmcnt(0)
	s_barrier
	s_setprio 1
	s_waitcnt lgkmcnt(0)
	v_mfma_f32_16x16x32_bf16 v[134:137], v[16:19], v[188:191], v[134:137]
	v_mfma_f32_16x16x32_bf16 v[130:133], v[138:141], v[188:191], v[130:133]
	v_mfma_f32_16x16x32_bf16 v[118:121], v[16:19], v[196:199], v[118:121]
	v_mfma_f32_16x16x32_bf16 v[114:117], v[138:141], v[196:199], v[114:117]
	v_mfma_f32_16x16x32_bf16 v[102:105], v[16:19], v[204:207], v[102:105]
	v_mfma_f32_16x16x32_bf16 v[98:101], v[138:141], v[204:207], v[98:101]
	v_mfma_f32_16x16x32_bf16 v[84:87], v[16:19], v[238:241], v[84:87]
	v_mfma_f32_16x16x32_bf16 v[80:83], v[138:141], v[238:241], v[80:83]
	v_mfma_f32_16x16x32_bf16 v[134:137], v[20:23], v[192:195], v[134:137]
	v_mfma_f32_16x16x32_bf16 v[130:133], v[142:145], v[192:195], v[130:133]
	v_mfma_f32_16x16x32_bf16 v[118:121], v[20:23], v[200:203], v[118:121]
	v_mfma_f32_16x16x32_bf16 v[114:117], v[142:145], v[200:203], v[114:117]
	v_mfma_f32_16x16x32_bf16 v[102:105], v[20:23], v[234:237], v[102:105]
	v_mfma_f32_16x16x32_bf16 v[98:101], v[142:145], v[234:237], v[98:101]
	v_mfma_f32_16x16x32_bf16 v[84:87], v[20:23], v[242:245], v[84:87]
	v_mfma_f32_16x16x32_bf16 v[80:83], v[142:145], v[242:245], v[80:83]
	s_setprio 0
	s_setprio 1
	v_mfma_f32_16x16x32_bf16 v[126:129], v[146:149], v[188:191], v[126:129]
	v_mfma_f32_16x16x32_bf16 v[122:125], v[180:183], v[188:191], v[122:125]
	v_mfma_f32_16x16x32_bf16 v[110:113], v[146:149], v[196:199], v[110:113]
	v_mfma_f32_16x16x32_bf16 v[106:109], v[180:183], v[196:199], v[106:109]
	v_mfma_f32_16x16x32_bf16 v[92:95], v[146:149], v[204:207], v[92:95]
	v_mfma_f32_16x16x32_bf16 v[88:91], v[180:183], v[204:207], v[88:91]
	v_mfma_f32_16x16x32_bf16 v[76:79], v[146:149], v[238:241], v[76:79]
	v_mfma_f32_16x16x32_bf16 v[72:75], v[180:183], v[238:241], v[72:75]
	v_mfma_f32_16x16x32_bf16 v[126:129], v[150:153], v[192:195], v[126:129]
	v_mfma_f32_16x16x32_bf16 v[122:125], v[184:187], v[192:195], v[122:125]
	v_mfma_f32_16x16x32_bf16 v[110:113], v[150:153], v[200:203], v[110:113]
	v_mfma_f32_16x16x32_bf16 v[106:109], v[184:187], v[200:203], v[106:109]
	v_mfma_f32_16x16x32_bf16 v[92:95], v[150:153], v[234:237], v[92:95]
	v_mfma_f32_16x16x32_bf16 v[88:91], v[184:187], v[234:237], v[88:91]
	v_mfma_f32_16x16x32_bf16 v[76:79], v[150:153], v[242:245], v[76:79]
	v_mfma_f32_16x16x32_bf16 v[72:75], v[184:187], v[242:245], v[72:75]
	s_setprio 0
	s_barrier
	s_add_i32 s14, s67, s58
	s_add_i32 m0, s14, 0xffffff80
	ds_read_b128 v[188:191], v231 offset:49152
	ds_read_b128 v[192:195], v231 offset:50176
	ds_read_b128 v[196:199], v231 offset:51200
	ds_read_b128 v[200:203], v231 offset:52224
	ds_read_b128 v[204:207], v231 offset:53248
	ds_read_b128 v[234:237], v231 offset:54272
	ds_read_b128 v[238:241], v231 offset:55296
	ds_read_b128 v[242:245], v231 offset:56320
	global_load_lds_dwordx4 v156, s[12:13] offset:128
	s_add_i32 m0, s14, 0x1f80
	s_add_i32 s14, s23, s58
	global_load_lds_dwordx4 v160, s[12:13] offset:128
	s_add_u32 s12, s12, 0x10080
	s_addc_u32 s13, s13, 0
	s_mov_b32 m0, s14
	s_nop 0
	global_load_lds_dwordx4 v156, s[12:13]
	s_add_i32 m0, s14, 0x2000
	s_nop 0
	global_load_lds_dwordx4 v160, s[12:13]
	s_add_i32 m0, s96, 0xffffff80
	s_nop 0
	global_load_lds_dwordx4 v154, s[26:27] offset:128
	s_add_i32 m0, s36, 0xffffff80
	s_nop 0
	global_load_lds_dwordx4 v158, s[26:27] offset:128
	s_waitcnt vmcnt(8)
	s_waitcnt lgkmcnt(0)
	s_barrier
	s_setprio 1
	s_waitcnt lgkmcnt(0)
	v_mfma_f32_16x16x32_bf16 v[68:71], v[16:19], v[188:191], v[68:71]
	v_mfma_f32_16x16x32_bf16 v[52:55], v[16:19], v[196:199], v[52:55]
	v_mfma_f32_16x16x32_bf16 v[36:39], v[16:19], v[204:207], v[36:39]
	v_mfma_f32_16x16x32_bf16 v[0:3], v[16:19], v[238:241], v[0:3]
	v_mfma_f32_16x16x32_bf16 v[68:71], v[20:23], v[192:195], v[68:71]
	v_mfma_f32_16x16x32_bf16 v[64:67], v[138:141], v[188:191], v[64:67]
	v_mfma_f32_16x16x32_bf16 v[52:55], v[20:23], v[200:203], v[52:55]
	v_mfma_f32_16x16x32_bf16 v[48:51], v[138:141], v[196:199], v[48:51]
	v_mfma_f32_16x16x32_bf16 v[36:39], v[20:23], v[234:237], v[36:39]
	v_mfma_f32_16x16x32_bf16 v[32:35], v[138:141], v[204:207], v[32:35]
	v_mfma_f32_16x16x32_bf16 v[20:23], v[20:23], v[242:245], v[0:3]
	v_mfma_f32_16x16x32_bf16 v[0:3], v[138:141], v[238:241], v[4:7]
	v_mfma_f32_16x16x32_bf16 v[64:67], v[142:145], v[192:195], v[64:67]
	v_mfma_f32_16x16x32_bf16 v[48:51], v[142:145], v[200:203], v[48:51]
	v_mfma_f32_16x16x32_bf16 v[32:35], v[142:145], v[234:237], v[32:35]
	v_mfma_f32_16x16x32_bf16 v[16:19], v[142:145], v[242:245], v[0:3]
	s_setprio 0
	s_setprio 1
	v_mfma_f32_16x16x32_bf16 v[0:3], v[146:149], v[188:191], v[60:63]
	v_mfma_f32_16x16x32_bf16 v[60:63], v[150:153], v[192:195], v[0:3]
	v_mfma_f32_16x16x32_bf16 v[0:3], v[180:183], v[188:191], v[56:59]
	v_mfma_f32_16x16x32_bf16 v[56:59], v[184:187], v[192:195], v[0:3]
	v_mfma_f32_16x16x32_bf16 v[0:3], v[146:149], v[196:199], v[44:47]
	v_mfma_f32_16x16x32_bf16 v[44:47], v[150:153], v[200:203], v[0:3]
	v_mfma_f32_16x16x32_bf16 v[0:3], v[180:183], v[196:199], v[40:43]
	v_mfma_f32_16x16x32_bf16 v[40:43], v[184:187], v[200:203], v[0:3]
	v_mfma_f32_16x16x32_bf16 v[0:3], v[146:149], v[204:207], v[28:31]
	v_mfma_f32_16x16x32_bf16 v[28:31], v[150:153], v[234:237], v[0:3]
	v_mfma_f32_16x16x32_bf16 v[0:3], v[180:183], v[204:207], v[24:27]
	v_mfma_f32_16x16x32_bf16 v[24:27], v[184:187], v[234:237], v[0:3]
	v_mfma_f32_16x16x32_bf16 v[0:3], v[146:149], v[238:241], v[12:15]
	v_mfma_f32_16x16x32_bf16 v[12:15], v[150:153], v[242:245], v[0:3]
	v_mfma_f32_16x16x32_bf16 v[0:3], v[180:183], v[238:241], v[8:11]
	v_mfma_f32_16x16x32_bf16 v[8:11], v[184:187], v[242:245], v[0:3]
	s_setprio 0
	s_barrier
	s_add_i32 s22, s22, 2
	s_add_u32 s2, s2, 0x100
	s_addc_u32 s3, s3, 0
	s_add_u32 s20, s20, 0x100
	s_addc_u32 s21, s21, 0
	.p2align 6
.LBB0_405:
	s_add_u32 s12, s2, 0xfffc0080
	s_addc_u32 s13, s3, -1
	s_add_i32 s23, 0, 0x10000
	s_cmp_eq_u32 s22, 12
	s_cselect_b32 s15, s16, s13
	s_cselect_b32 s14, s17, s12
	s_cselect_b32 s13, s18, s21
	s_cselect_b32 s12, s19, s20
	s_add_i32 s31, 0, 0x14000
	ds_read_b128 v[0:3], v253
	ds_read_b128 v[4:7], v253 offset:1024
	ds_read_b128 v[138:141], v253 offset:2048
	ds_read_b128 v[142:145], v253 offset:3072
	ds_read_b128 v[146:149], v253 offset:16384
	ds_read_b128 v[150:153], v253 offset:17408
	ds_read_b128 v[180:183], v253 offset:18432
	ds_read_b128 v[184:187], v253 offset:19456
	s_add_i32 m0, s69, 0xc000
	ds_read_b128 v[188:191], v231
	ds_read_b128 v[192:195], v231 offset:1024
	ds_read_b128 v[196:199], v231 offset:2048
	ds_read_b128 v[200:203], v231 offset:3072
	ds_read_b128 v[204:207], v231 offset:4096
	ds_read_b128 v[234:237], v231 offset:5120
	ds_read_b128 v[238:241], v231 offset:6144
	ds_read_b128 v[242:245], v231 offset:7168
	global_load_lds_dwordx4 v166, s[2:3]
	s_add_i32 m0, s69, 0xe000
	s_nop 0
	global_load_lds_dwordx4 v168, s[2:3]
	s_waitcnt vmcnt(8)
	s_waitcnt lgkmcnt(0)
	s_barrier
	s_setprio 1
	s_waitcnt lgkmcnt(0)
	v_mfma_f32_16x16x32_bf16 v[134:137], v[0:3], v[188:191], v[134:137]
	v_mfma_f32_16x16x32_bf16 v[130:133], v[138:141], v[188:191], v[130:133]
	v_mfma_f32_16x16x32_bf16 v[118:121], v[0:3], v[196:199], v[118:121]
	v_mfma_f32_16x16x32_bf16 v[114:117], v[138:141], v[196:199], v[114:117]
	v_mfma_f32_16x16x32_bf16 v[102:105], v[0:3], v[204:207], v[102:105]
	v_mfma_f32_16x16x32_bf16 v[98:101], v[138:141], v[204:207], v[98:101]
	v_mfma_f32_16x16x32_bf16 v[84:87], v[0:3], v[238:241], v[84:87]
	v_mfma_f32_16x16x32_bf16 v[80:83], v[138:141], v[238:241], v[80:83]
	v_mfma_f32_16x16x32_bf16 v[134:137], v[4:7], v[192:195], v[134:137]
	v_mfma_f32_16x16x32_bf16 v[130:133], v[142:145], v[192:195], v[130:133]
	v_mfma_f32_16x16x32_bf16 v[118:121], v[4:7], v[200:203], v[118:121]
	v_mfma_f32_16x16x32_bf16 v[114:117], v[142:145], v[200:203], v[114:117]
	v_mfma_f32_16x16x32_bf16 v[102:105], v[4:7], v[234:237], v[102:105]
	v_mfma_f32_16x16x32_bf16 v[98:101], v[142:145], v[234:237], v[98:101]
	v_mfma_f32_16x16x32_bf16 v[84:87], v[4:7], v[242:245], v[84:87]
	v_mfma_f32_16x16x32_bf16 v[80:83], v[142:145], v[242:245], v[80:83]
	s_setprio 0
	s_setprio 1
	v_mfma_f32_16x16x32_bf16 v[126:129], v[146:149], v[188:191], v[126:129]
	v_mfma_f32_16x16x32_bf16 v[122:125], v[180:183], v[188:191], v[122:125]
	v_mfma_f32_16x16x32_bf16 v[110:113], v[146:149], v[196:199], v[110:113]
	v_mfma_f32_16x16x32_bf16 v[106:109], v[180:183], v[196:199], v[106:109]
	v_mfma_f32_16x16x32_bf16 v[92:95], v[146:149], v[204:207], v[92:95]
	v_mfma_f32_16x16x32_bf16 v[88:91], v[180:183], v[204:207], v[88:91]
	v_mfma_f32_16x16x32_bf16 v[76:79], v[146:149], v[238:241], v[76:79]
	v_mfma_f32_16x16x32_bf16 v[72:75], v[180:183], v[238:241], v[72:75]
	v_mfma_f32_16x16x32_bf16 v[126:129], v[150:153], v[192:195], v[126:129]
	v_mfma_f32_16x16x32_bf16 v[122:125], v[184:187], v[192:195], v[122:125]
	v_mfma_f32_16x16x32_bf16 v[110:113], v[150:153], v[200:203], v[110:113]
	v_mfma_f32_16x16x32_bf16 v[106:109], v[184:187], v[200:203], v[106:109]
	v_mfma_f32_16x16x32_bf16 v[92:95], v[150:153], v[234:237], v[92:95]
	v_mfma_f32_16x16x32_bf16 v[88:91], v[184:187], v[234:237], v[88:91]
	v_mfma_f32_16x16x32_bf16 v[76:79], v[150:153], v[242:245], v[76:79]
	v_mfma_f32_16x16x32_bf16 v[72:75], v[184:187], v[242:245], v[72:75]
	s_setprio 0
	s_barrier
	s_add_i32 s23, s23, s58
	s_mov_b32 m0, s23
	ds_read_b128 v[188:191], v231 offset:16384
	ds_read_b128 v[192:195], v231 offset:17408
	ds_read_b128 v[196:199], v231 offset:18432
	ds_read_b128 v[200:203], v231 offset:19456
	ds_read_b128 v[204:207], v231 offset:20480
	ds_read_b128 v[234:237], v231 offset:21504
	ds_read_b128 v[238:241], v231 offset:22528
	ds_read_b128 v[242:245], v231 offset:23552
	global_load_lds_dwordx4 v156, s[12:13]
	s_add_i32 m0, s23, 0x2000
	s_add_u32 s26, s12, 0x10000
	s_addc_u32 s27, s13, 0
	s_add_i32 s23, s31, s58
	global_load_lds_dwordx4 v160, s[12:13]
	s_mov_b32 m0, s23
	s_nop 0
	global_load_lds_dwordx4 v156, s[26:27]
	s_add_i32 m0, s23, 0x2000
	s_nop 0
	global_load_lds_dwordx4 v160, s[26:27]
	s_mov_b64 s[26:27], s[14:15]
	s_mov_b32 m0, s69
	s_nop 0
	global_load_lds_dwordx4 v154, s[14:15]
	s_mov_b32 m0, s70
	s_nop 0
	global_load_lds_dwordx4 v158, s[14:15]
	s_waitcnt vmcnt(8)
	s_waitcnt lgkmcnt(0)
	s_barrier
	s_setprio 1
	s_waitcnt lgkmcnt(0)
	v_mfma_f32_16x16x32_bf16 v[68:71], v[0:3], v[188:191], v[68:71]
	v_mfma_f32_16x16x32_bf16 v[64:67], v[138:141], v[188:191], v[64:67]
	v_mfma_f32_16x16x32_bf16 v[52:55], v[0:3], v[196:199], v[52:55]
	v_mfma_f32_16x16x32_bf16 v[48:51], v[138:141], v[196:199], v[48:51]
	v_mfma_f32_16x16x32_bf16 v[36:39], v[0:3], v[204:207], v[36:39]
	v_mfma_f32_16x16x32_bf16 v[32:35], v[138:141], v[204:207], v[32:35]
	v_mfma_f32_16x16x32_bf16 v[0:3], v[0:3], v[238:241], v[20:23]
	v_mfma_f32_16x16x32_bf16 v[68:71], v[4:7], v[192:195], v[68:71]
	v_mfma_f32_16x16x32_bf16 v[64:67], v[142:145], v[192:195], v[64:67]
	v_mfma_f32_16x16x32_bf16 v[52:55], v[4:7], v[200:203], v[52:55]
	v_mfma_f32_16x16x32_bf16 v[48:51], v[142:145], v[200:203], v[48:51]
	v_mfma_f32_16x16x32_bf16 v[36:39], v[4:7], v[234:237], v[36:39]
	v_mfma_f32_16x16x32_bf16 v[32:35], v[142:145], v[234:237], v[32:35]
	v_mfma_f32_16x16x32_bf16 v[0:3], v[4:7], v[242:245], v[0:3]
	v_mfma_f32_16x16x32_bf16 v[4:7], v[138:141], v[238:241], v[16:19]
	v_mfma_f32_16x16x32_bf16 v[4:7], v[142:145], v[242:245], v[4:7]
	s_setprio 0
	s_setprio 1
	v_mfma_f32_16x16x32_bf16 v[16:19], v[146:149], v[188:191], v[60:63]
	v_mfma_f32_16x16x32_bf16 v[60:63], v[150:153], v[192:195], v[16:19]
	v_mfma_f32_16x16x32_bf16 v[16:19], v[180:183], v[188:191], v[56:59]
	v_mfma_f32_16x16x32_bf16 v[56:59], v[184:187], v[192:195], v[16:19]
	v_mfma_f32_16x16x32_bf16 v[16:19], v[146:149], v[196:199], v[44:47]
	v_mfma_f32_16x16x32_bf16 v[44:47], v[150:153], v[200:203], v[16:19]
	v_mfma_f32_16x16x32_bf16 v[16:19], v[180:183], v[196:199], v[40:43]
	v_mfma_f32_16x16x32_bf16 v[40:43], v[184:187], v[200:203], v[16:19]
	v_mfma_f32_16x16x32_bf16 v[16:19], v[146:149], v[204:207], v[28:31]
	v_mfma_f32_16x16x32_bf16 v[28:31], v[150:153], v[234:237], v[16:19]
	v_mfma_f32_16x16x32_bf16 v[16:19], v[180:183], v[204:207], v[24:27]
	v_mfma_f32_16x16x32_bf16 v[12:15], v[146:149], v[238:241], v[12:15]
	v_mfma_f32_16x16x32_bf16 v[8:11], v[180:183], v[238:241], v[8:11]
	v_mfma_f32_16x16x32_bf16 v[24:27], v[184:187], v[234:237], v[16:19]
	v_mfma_f32_16x16x32_bf16 v[12:15], v[150:153], v[242:245], v[12:15]
	v_mfma_f32_16x16x32_bf16 v[8:11], v[184:187], v[242:245], v[8:11]
	s_setprio 0
	s_barrier
	s_add_i32 s23, 0, 0x1c000
	ds_read_b128 v[16:19], v253 offset:32768
	ds_read_b128 v[20:23], v253 offset:33792
	ds_read_b128 v[138:141], v253 offset:34816
	ds_read_b128 v[142:145], v253 offset:35840
	ds_read_b128 v[146:149], v253 offset:49152
	ds_read_b128 v[150:153], v253 offset:50176
	ds_read_b128 v[180:183], v253 offset:51200
	ds_read_b128 v[184:187], v253 offset:52224
	s_add_u32 s14, s14, 0x40000
	s_addc_u32 s15, s15, 0
	s_mov_b32 m0, s71
	ds_read_b128 v[188:191], v231 offset:32768
	ds_read_b128 v[192:195], v231 offset:33792
	ds_read_b128 v[196:199], v231 offset:34816
	ds_read_b128 v[200:203], v231 offset:35840
	ds_read_b128 v[204:207], v231 offset:36864
	ds_read_b128 v[234:237], v231 offset:37888
	ds_read_b128 v[238:241], v231 offset:38912
	ds_read_b128 v[242:245], v231 offset:39936
	global_load_lds_dwordx4 v154, s[14:15]
	s_mov_b32 m0, s76
	s_nop 0
	global_load_lds_dwordx4 v158, s[14:15]
	s_waitcnt vmcnt(8)
	s_waitcnt lgkmcnt(0)
	s_barrier
	s_setprio 1
	s_waitcnt lgkmcnt(0)
	v_mfma_f32_16x16x32_bf16 v[134:137], v[16:19], v[188:191], v[134:137]
	v_mfma_f32_16x16x32_bf16 v[130:133], v[138:141], v[188:191], v[130:133]
	v_mfma_f32_16x16x32_bf16 v[118:121], v[16:19], v[196:199], v[118:121]
	v_mfma_f32_16x16x32_bf16 v[114:117], v[138:141], v[196:199], v[114:117]
	v_mfma_f32_16x16x32_bf16 v[102:105], v[16:19], v[204:207], v[102:105]
	v_mfma_f32_16x16x32_bf16 v[98:101], v[138:141], v[204:207], v[98:101]
	v_mfma_f32_16x16x32_bf16 v[84:87], v[16:19], v[238:241], v[84:87]
	v_mfma_f32_16x16x32_bf16 v[80:83], v[138:141], v[238:241], v[80:83]
	v_mfma_f32_16x16x32_bf16 v[134:137], v[20:23], v[192:195], v[134:137]
	v_mfma_f32_16x16x32_bf16 v[130:133], v[142:145], v[192:195], v[130:133]
	v_mfma_f32_16x16x32_bf16 v[118:121], v[20:23], v[200:203], v[118:121]
	v_mfma_f32_16x16x32_bf16 v[114:117], v[142:145], v[200:203], v[114:117]
	v_mfma_f32_16x16x32_bf16 v[102:105], v[20:23], v[234:237], v[102:105]
	v_mfma_f32_16x16x32_bf16 v[98:101], v[142:145], v[234:237], v[98:101]
	v_mfma_f32_16x16x32_bf16 v[84:87], v[20:23], v[242:245], v[84:87]
	v_mfma_f32_16x16x32_bf16 v[80:83], v[142:145], v[242:245], v[80:83]
	s_setprio 0
	s_setprio 1
	v_mfma_f32_16x16x32_bf16 v[126:129], v[146:149], v[188:191], v[126:129]
	v_mfma_f32_16x16x32_bf16 v[122:125], v[180:183], v[188:191], v[122:125]
	v_mfma_f32_16x16x32_bf16 v[110:113], v[146:149], v[196:199], v[110:113]
	v_mfma_f32_16x16x32_bf16 v[106:109], v[180:183], v[196:199], v[106:109]
	v_mfma_f32_16x16x32_bf16 v[92:95], v[146:149], v[204:207], v[92:95]
	v_mfma_f32_16x16x32_bf16 v[88:91], v[180:183], v[204:207], v[88:91]
	v_mfma_f32_16x16x32_bf16 v[76:79], v[146:149], v[238:241], v[76:79]
	v_mfma_f32_16x16x32_bf16 v[72:75], v[180:183], v[238:241], v[72:75]
	v_mfma_f32_16x16x32_bf16 v[126:129], v[150:153], v[192:195], v[126:129]
	v_mfma_f32_16x16x32_bf16 v[122:125], v[184:187], v[192:195], v[122:125]
	v_mfma_f32_16x16x32_bf16 v[110:113], v[150:153], v[200:203], v[110:113]
	v_mfma_f32_16x16x32_bf16 v[106:109], v[184:187], v[200:203], v[106:109]
	v_mfma_f32_16x16x32_bf16 v[92:95], v[150:153], v[234:237], v[92:95]
	v_mfma_f32_16x16x32_bf16 v[88:91], v[184:187], v[234:237], v[88:91]
	v_mfma_f32_16x16x32_bf16 v[76:79], v[150:153], v[242:245], v[76:79]
	v_mfma_f32_16x16x32_bf16 v[72:75], v[184:187], v[242:245], v[72:75]
	s_setprio 0
	s_barrier
	s_add_i32 s14, s67, s58
	s_add_i32 m0, s14, 0xffffff80
	ds_read_b128 v[188:191], v231 offset:49152
	ds_read_b128 v[192:195], v231 offset:50176
	ds_read_b128 v[196:199], v231 offset:51200
	ds_read_b128 v[200:203], v231 offset:52224
	ds_read_b128 v[204:207], v231 offset:53248
	ds_read_b128 v[234:237], v231 offset:54272
	ds_read_b128 v[238:241], v231 offset:55296
	ds_read_b128 v[242:245], v231 offset:56320
	global_load_lds_dwordx4 v156, s[12:13] offset:128
	s_add_i32 m0, s14, 0x1f80
	s_add_i32 s14, s23, s58
	global_load_lds_dwordx4 v160, s[12:13] offset:128
	s_add_u32 s12, s12, 0x10080
	s_addc_u32 s13, s13, 0
	s_mov_b32 m0, s14
	s_nop 0
	global_load_lds_dwordx4 v156, s[12:13]
	s_add_i32 m0, s14, 0x2000
	s_nop 0
	global_load_lds_dwordx4 v160, s[12:13]
	s_add_i32 m0, s96, 0xffffff80
	s_nop 0
	global_load_lds_dwordx4 v154, s[26:27] offset:128
	s_add_i32 m0, s36, 0xffffff80
	s_nop 0
	global_load_lds_dwordx4 v158, s[26:27] offset:128
	s_waitcnt vmcnt(8)
	s_waitcnt lgkmcnt(0)
	s_barrier
	s_setprio 1
	s_waitcnt lgkmcnt(0)
	v_mfma_f32_16x16x32_bf16 v[68:71], v[16:19], v[188:191], v[68:71]
	v_mfma_f32_16x16x32_bf16 v[52:55], v[16:19], v[196:199], v[52:55]
	v_mfma_f32_16x16x32_bf16 v[36:39], v[16:19], v[204:207], v[36:39]
	v_mfma_f32_16x16x32_bf16 v[0:3], v[16:19], v[238:241], v[0:3]
	v_mfma_f32_16x16x32_bf16 v[68:71], v[20:23], v[192:195], v[68:71]
	v_mfma_f32_16x16x32_bf16 v[64:67], v[138:141], v[188:191], v[64:67]
	v_mfma_f32_16x16x32_bf16 v[52:55], v[20:23], v[200:203], v[52:55]
	v_mfma_f32_16x16x32_bf16 v[48:51], v[138:141], v[196:199], v[48:51]
	v_mfma_f32_16x16x32_bf16 v[36:39], v[20:23], v[234:237], v[36:39]
	v_mfma_f32_16x16x32_bf16 v[32:35], v[138:141], v[204:207], v[32:35]
	v_mfma_f32_16x16x32_bf16 v[20:23], v[20:23], v[242:245], v[0:3]
	v_mfma_f32_16x16x32_bf16 v[0:3], v[138:141], v[238:241], v[4:7]
	v_mfma_f32_16x16x32_bf16 v[64:67], v[142:145], v[192:195], v[64:67]
	v_mfma_f32_16x16x32_bf16 v[48:51], v[142:145], v[200:203], v[48:51]
	v_mfma_f32_16x16x32_bf16 v[32:35], v[142:145], v[234:237], v[32:35]
	v_mfma_f32_16x16x32_bf16 v[16:19], v[142:145], v[242:245], v[0:3]
	s_setprio 0
	s_setprio 1
	v_mfma_f32_16x16x32_bf16 v[0:3], v[146:149], v[188:191], v[60:63]
	v_mfma_f32_16x16x32_bf16 v[60:63], v[150:153], v[192:195], v[0:3]
	v_mfma_f32_16x16x32_bf16 v[0:3], v[180:183], v[188:191], v[56:59]
	v_mfma_f32_16x16x32_bf16 v[56:59], v[184:187], v[192:195], v[0:3]
	v_mfma_f32_16x16x32_bf16 v[0:3], v[146:149], v[196:199], v[44:47]
	v_mfma_f32_16x16x32_bf16 v[44:47], v[150:153], v[200:203], v[0:3]
	v_mfma_f32_16x16x32_bf16 v[0:3], v[180:183], v[196:199], v[40:43]
	v_mfma_f32_16x16x32_bf16 v[40:43], v[184:187], v[200:203], v[0:3]
	v_mfma_f32_16x16x32_bf16 v[0:3], v[146:149], v[204:207], v[28:31]
	v_mfma_f32_16x16x32_bf16 v[28:31], v[150:153], v[234:237], v[0:3]
	v_mfma_f32_16x16x32_bf16 v[0:3], v[180:183], v[204:207], v[24:27]
	v_mfma_f32_16x16x32_bf16 v[24:27], v[184:187], v[234:237], v[0:3]
	v_mfma_f32_16x16x32_bf16 v[0:3], v[146:149], v[238:241], v[12:15]
	v_mfma_f32_16x16x32_bf16 v[12:15], v[150:153], v[242:245], v[0:3]
	v_mfma_f32_16x16x32_bf16 v[0:3], v[180:183], v[238:241], v[8:11]
	v_mfma_f32_16x16x32_bf16 v[8:11], v[184:187], v[242:245], v[0:3]
	s_setprio 0
	s_barrier
	s_add_i32 s22, s22, 2
	s_add_u32 s2, s2, 0x100
	s_addc_u32 s3, s3, 0
	s_add_u32 s20, s20, 0x100
	s_addc_u32 s21, s21, 0
	s_cmp_gt_u32 s22, 13
	s_cbranch_scc0 .LBB0_405
	s_and_b64 vcc, exec, s[42:43]
	s_cbranch_vccz .LBB0_418
	s_barrier
	s_andn2_b64 vcc, exec, s[38:39]
	s_mov_b64 s[2:3], -1
	s_cbranch_vccz .LBB0_419

.LBB0_733:
	s_and_b32 s3, s6, 3
	s_waitcnt lgkmcnt(0)
	s_bfe_u32 s16, s61, 0x70001
	s_add_i32 m0, s79, 0x18000
	v_lshl_add_u64 v[6:7], v[6:7], 0, s[62:63]
	s_lshl_b32 s20, s7, 6
	s_lshl_b32 s7, s7, 13
	s_lshl_b32 s14, s3, 12
	s_and_b32 s15, s61, 0xff
	s_lshl_b32 s17, s16, 20
	s_lshl_b32 s18, s16, 19
	s_waitcnt vmcnt(2)
	s_barrier
	global_load_lds_dwordx4 v[6:7], off
	v_lshl_add_u64 v[4:5], v[4:5], 0, s[62:63]
	s_add_i32 m0, s79, 0x1a000
	s_add_i32 s21, s79, 0x8000
	s_add_i32 s61, s79, 0xa000
	global_load_lds_dwordx4 v[4:5], off
	v_lshl_add_u64 v[2:3], v[2:3], 0, s[62:63]
	s_mov_b32 m0, s21
	s_add_u32 s8, s12, 0x10080
	global_load_lds_dwordx4 v[2:3], off
	v_lshl_add_u64 v[2:3], v[8:9], 0, s[62:63]
	s_mov_b32 m0, s61
	s_addc_u32 s9, s13, 0
	global_load_lds_dwordx4 v[2:3], off
	s_add_i32 m0, s79, 0x1c000
	v_lshl_add_u64 v[2:3], s[8:9], 0, v[156:157]
	global_load_lds_dwordx4 v[2:3], off
	v_lshl_add_u64 v[2:3], s[8:9], 0, v[160:161]
	s_add_i32 m0, s79, 0x1e000
	v_and_b32_e32 v163, 15, v0
	global_load_lds_dwordx4 v[2:3], off
	v_bfe_u32 v3, v0, 4, 2
	v_lshlrev_b32_e32 v2, 4, v3
	v_lshlrev_b32_e32 v6, 2, v0
	v_lshl_or_b32 v2, v163, 6, v2
	v_and_b32_e32 v162, 32, v6
	v_bitop3_b32 v7, v2, s7, v162 bitop3:0xde
	s_mul_i32 s7, s15, 0x90000
	v_writelane_b32 v252, s7, 35
	s_mul_i32 s7, s16, 0x1e0000
	v_writelane_b32 v252, s7, 26
	s_mul_i32 s7, s16, 0xf0000
	s_cmp_lt_i32 s6, 4
	v_bitop3_b32 v165, v2, s14, v162 bitop3:0xde
	v_add_u32_e32 v253, 0x10000, v165
	s_mul_i32 s90, s15, 0x10200
	s_mul_i32 s8, s15, 0x24000
	v_writelane_b32 v252, s7, 36
	s_cselect_b64 s[14:15], -1, 0
	v_writelane_b32 v252, s14, 38
	s_cmp_eq_u32 s6, 4
	s_cselect_b64 s[6:7], -1, 0
	v_writelane_b32 v252, s15, 39
	v_writelane_b32 v252, s6, 40
	s_cmpk_lt_u32 s11, 0x100
	v_lshlrev_b32_e32 v5, 3, v3
	v_writelane_b32 v252, s7, 41
	s_cselect_b64 s[6:7], -1, 0
	s_lshl_b32 s96, s10, 3
	v_lshlrev_b32_e32 v209, 5, v3
	v_cvt_f32_ubyte0_e32 v3, s96
	v_rcp_iflag_f32_e32 v3, v3
	v_writelane_b32 v252, s6, 30
	v_and_b32_e32 v207, 7, v0
	v_lshl_add_u64 v[0:1], v[0:1], 0, s[90:91]
	v_mul_f32_e32 v3, 0x4f7ffffe, v3
	v_writelane_b32 v252, s7, 31
	s_add_i32 s9, s20, 0x80
	v_cvt_u32_f32_e32 v3, v3
	v_lshlrev_b64 v[166:167], 4, v[0:1]
	v_lshlrev_b32_e32 v0, 14, v10
	v_lshl_or_b32 v206, s3, 6, v5
	v_writelane_b32 v252, s9, 24
	s_lshl_b32 s3, s3, 8
	v_and_b32_e32 v0, 0xffff8000, v0
	v_writelane_b32 v252, s3, 42
	s_ashr_i32 s3, s25, 31
	v_lshl_add_u32 v0, v11, 11, v0
	v_and_b32_e32 v1, 1, v10
	v_writelane_b32 v252, s3, 22
	s_and_b32 s9, s28, 4
	v_lshl_or_b32 v0, v1, 6, v0
	v_writelane_b32 v252, s9, 43
	s_sub_i32 s9, 0, s96
	v_readfirstlane_b32 s10, v3
	v_lshl_add_u32 v168, v12, 1, v0
	v_lshlrev_b32_e32 v0, 14, v13
	s_lshr_b32 s3, s28, 3
	s_mul_i32 s9, s9, s10
	v_and_b32_e32 v0, 0xffff8000, v0
	s_waitcnt vmcnt(6)
	v_writelane_b32 v252, s3, 44
	s_add_i32 s3, s3, 1
	s_mul_hi_u32 s9, s10, s9
	v_lshl_add_u32 v0, v14, 11, v0
	v_and_b32_e32 v1, 1, v13
	v_or_b32_e32 v4, s20, v163
	v_and_b32_e32 v2, 0xfc, v6
	v_writelane_b32 v252, s3, 45
	s_add_i32 s9, s10, s9
	v_lshl_or_b32 v0, v1, 6, v0
	v_cmp_gt_u32_e64 s[6:7], 8, v163
	v_lshlrev_b32_e32 v208, 4, v4
	v_lshlrev_b32_e32 v164, 8, v163
	s_ashr_i32 s68, s80, 31
	s_mov_b32 s31, s91
	s_mov_b32 s29, s91
	s_mov_b32 s3, 0
	v_writelane_b32 v252, s9, 46
	v_mov_b32_e32 v169, v97
	v_lshl_add_u32 v170, v15, 1, v0
	v_mov_b32_e32 v171, v97
	s_lshl_b32 s8, s8, 2
	v_lshlrev_b32_e32 v180, 2, v2
	v_add_u32_e32 v221, 0, v7
	s_lshl_b32 s58, s17, 2
	s_lshl_b32 s60, s18, 2
	s_movk_i32 s86, 0x77f
	s_barrier
	v_writelane_b32 v252, s8, 47
	s_branch .LBB0_736

.LBB0_749:
	s_ashr_i32 s49, s48, 31
	s_waitcnt lgkmcnt(0)
	s_lshl_b64 s[14:15], s[48:49], 19
	s_add_u32 s38, s22, s14
	s_addc_u32 s39, s23, s15
	s_and_b64 s[14:15], s[8:9], exec
	s_cselect_b32 s3, s39, s5
	s_cselect_b32 s16, s38, s4
	s_ashr_i32 s35, s34, 31
	s_lshl_b64 s[14:15], s[34:35], 19
	s_add_u32 s40, s56, s14
	s_addc_u32 s41, s57, s15
	s_and_b64 s[14:15], s[8:9], exec
	s_cselect_b32 s17, s41, s13
	s_cselect_b32 s18, s40, s12
	s_add_u32 s4, s4, 0x40080
	s_addc_u32 s5, s5, 0
	s_add_u32 s19, s12, 0x100
	s_addc_u32 s26, s13, 0
	s_mov_b32 s27, -2
	s_add_u32 s12, s4, 0xfffc0080
	s_addc_u32 s13, s5, -1
	s_add_i32 s33, 0, 0x10000
	s_cmp_eq_u32 s27, 12
	s_cselect_b32 s15, s3, s13
	s_cselect_b32 s14, s16, s12
	s_cselect_b32 s13, s17, s26
	s_cselect_b32 s12, s18, s19
	s_add_i32 s35, 0, 0x14000
	ds_read_b128 v[0:3], v253
	ds_read_b128 v[4:7], v253 offset:1024
	ds_read_b128 v[138:141], v253 offset:2048
	ds_read_b128 v[142:145], v253 offset:3072
	ds_read_b128 v[146:149], v253 offset:16384
	ds_read_b128 v[150:153], v253 offset:17408
	ds_read_b128 v[182:185], v253 offset:18432
	ds_read_b128 v[186:189], v253 offset:19456
	s_add_i32 m0, s79, 0xc000
	ds_read_b128 v[190:193], v221
	ds_read_b128 v[194:197], v221 offset:1024
	ds_read_b128 v[198:201], v221 offset:2048
	ds_read_b128 v[202:205], v221 offset:3072
	ds_read_b128 v[222:225], v221 offset:4096
	ds_read_b128 v[226:229], v221 offset:5120
	ds_read_b128 v[230:233], v221 offset:6144
	ds_read_b128 v[234:237], v221 offset:7168
	global_load_lds_dwordx4 v168, s[4:5]
	s_add_i32 m0, s79, 0xe000
	s_nop 0
	global_load_lds_dwordx4 v170, s[4:5]
	s_cmp_lg_u32 s100, 0
	s_cbranch_scc1 .Lpl_in_r1
	s_waitcnt vmcnt(8)
	s_branch .Lpl_in_j1

.Lpl_in_j1:
	s_waitcnt lgkmcnt(0)
	s_barrier
	s_setprio 1
	s_waitcnt lgkmcnt(0)
	v_mfma_f32_16x16x32_bf16 v[134:137], v[0:3], v[190:193], 0
	v_mfma_f32_16x16x32_bf16 v[130:133], v[138:141], v[190:193], 0
	v_mfma_f32_16x16x32_bf16 v[118:121], v[0:3], v[198:201], 0
	v_mfma_f32_16x16x32_bf16 v[114:117], v[138:141], v[198:201], 0
	v_mfma_f32_16x16x32_bf16 v[102:105], v[0:3], v[222:225], 0
	v_mfma_f32_16x16x32_bf16 v[98:101], v[138:141], v[222:225], 0
	v_mfma_f32_16x16x32_bf16 v[84:87], v[0:3], v[230:233], 0
	v_mfma_f32_16x16x32_bf16 v[80:83], v[138:141], v[230:233], 0
	v_mfma_f32_16x16x32_bf16 v[134:137], v[4:7], v[194:197], v[134:137]
	v_mfma_f32_16x16x32_bf16 v[130:133], v[142:145], v[194:197], v[130:133]
	v_mfma_f32_16x16x32_bf16 v[118:121], v[4:7], v[202:205], v[118:121]
	v_mfma_f32_16x16x32_bf16 v[114:117], v[142:145], v[202:205], v[114:117]
	v_mfma_f32_16x16x32_bf16 v[102:105], v[4:7], v[226:229], v[102:105]
	v_mfma_f32_16x16x32_bf16 v[98:101], v[142:145], v[226:229], v[98:101]
	v_mfma_f32_16x16x32_bf16 v[84:87], v[4:7], v[234:237], v[84:87]
	v_mfma_f32_16x16x32_bf16 v[80:83], v[142:145], v[234:237], v[80:83]
	s_setprio 0
	s_setprio 1
	v_mfma_f32_16x16x32_bf16 v[126:129], v[146:149], v[190:193], 0
	v_mfma_f32_16x16x32_bf16 v[122:125], v[182:185], v[190:193], 0
	v_mfma_f32_16x16x32_bf16 v[110:113], v[146:149], v[198:201], 0
	v_mfma_f32_16x16x32_bf16 v[106:109], v[182:185], v[198:201], 0
	v_mfma_f32_16x16x32_bf16 v[92:95], v[146:149], v[222:225], 0
	v_mfma_f32_16x16x32_bf16 v[88:91], v[182:185], v[222:225], 0
	v_mfma_f32_16x16x32_bf16 v[76:79], v[146:149], v[230:233], 0
	v_mfma_f32_16x16x32_bf16 v[72:75], v[182:185], v[230:233], 0
	v_mfma_f32_16x16x32_bf16 v[126:129], v[150:153], v[194:197], v[126:129]
	v_mfma_f32_16x16x32_bf16 v[122:125], v[186:189], v[194:197], v[122:125]
	v_mfma_f32_16x16x32_bf16 v[110:113], v[150:153], v[202:205], v[110:113]
	v_mfma_f32_16x16x32_bf16 v[106:109], v[186:189], v[202:205], v[106:109]
	v_mfma_f32_16x16x32_bf16 v[92:95], v[150:153], v[226:229], v[92:95]
	v_mfma_f32_16x16x32_bf16 v[88:91], v[186:189], v[226:229], v[88:91]
	v_mfma_f32_16x16x32_bf16 v[76:79], v[150:153], v[234:237], v[76:79]
	v_mfma_f32_16x16x32_bf16 v[72:75], v[186:189], v[234:237], v[72:75]
	s_setprio 0
	s_barrier
	s_add_i32 s33, s33, s78
	s_mov_b32 m0, s33
	ds_read_b128 v[190:193], v221 offset:16384
	ds_read_b128 v[194:197], v221 offset:17408
	ds_read_b128 v[198:201], v221 offset:18432
	ds_read_b128 v[202:205], v221 offset:19456
	ds_read_b128 v[222:225], v221 offset:20480
	ds_read_b128 v[226:229], v221 offset:21504
	ds_read_b128 v[230:233], v221 offset:22528
	ds_read_b128 v[234:237], v221 offset:23552
	global_load_lds_dwordx4 v156, s[12:13]
	s_add_i32 m0, s33, 0x2000
	s_add_u32 s42, s12, 0x10000
	s_addc_u32 s43, s13, 0
	s_add_i32 s33, s35, s78
	global_load_lds_dwordx4 v160, s[12:13]
	s_mov_b32 m0, s33
	s_nop 0
	global_load_lds_dwordx4 v156, s[42:43]
	s_add_i32 m0, s33, 0x2000
	s_nop 0
	global_load_lds_dwordx4 v160, s[42:43]
	s_mov_b64 s[42:43], s[14:15]
	s_mov_b32 m0, s79
	s_nop 0
	global_load_lds_dwordx4 v154, s[14:15]
	s_mov_b32 m0, s81
	s_nop 0
	global_load_lds_dwordx4 v158, s[14:15]
	s_cmp_lg_u32 s100, 0
	s_cbranch_scc1 .Lpl_in_r2
	s_waitcnt vmcnt(8)
	s_branch .Lpl_in_j2

.Lpl_in_j2:
	s_mov_b32 s100, 0
	s_waitcnt lgkmcnt(0)
	s_barrier
	s_setprio 1
	s_waitcnt lgkmcnt(0)
	v_mfma_f32_16x16x32_bf16 v[68:71], v[0:3], v[190:193], 0
	v_mfma_f32_16x16x32_bf16 v[64:67], v[138:141], v[190:193], 0
	v_mfma_f32_16x16x32_bf16 v[52:55], v[0:3], v[198:201], 0
	v_mfma_f32_16x16x32_bf16 v[48:51], v[138:141], v[198:201], 0
	v_mfma_f32_16x16x32_bf16 v[36:39], v[0:3], v[222:225], 0
	v_mfma_f32_16x16x32_bf16 v[32:35], v[138:141], v[222:225], 0
	v_mfma_f32_16x16x32_bf16 v[0:3], v[0:3], v[230:233], 0
	v_mfma_f32_16x16x32_bf16 v[68:71], v[4:7], v[194:197], v[68:71]
	v_mfma_f32_16x16x32_bf16 v[64:67], v[142:145], v[194:197], v[64:67]
	v_mfma_f32_16x16x32_bf16 v[52:55], v[4:7], v[202:205], v[52:55]
	v_mfma_f32_16x16x32_bf16 v[48:51], v[142:145], v[202:205], v[48:51]
	v_mfma_f32_16x16x32_bf16 v[36:39], v[4:7], v[226:229], v[36:39]
	v_mfma_f32_16x16x32_bf16 v[32:35], v[142:145], v[226:229], v[32:35]
	v_mfma_f32_16x16x32_bf16 v[0:3], v[4:7], v[234:237], v[0:3]
	v_mfma_f32_16x16x32_bf16 v[4:7], v[138:141], v[230:233], 0
	v_mfma_f32_16x16x32_bf16 v[4:7], v[142:145], v[234:237], v[4:7]
	s_setprio 0
	s_setprio 1
	v_mfma_f32_16x16x32_bf16 v[16:19], v[146:149], v[190:193], 0
	v_mfma_f32_16x16x32_bf16 v[60:63], v[150:153], v[194:197], v[16:19]
	v_mfma_f32_16x16x32_bf16 v[16:19], v[182:185], v[190:193], 0
	v_mfma_f32_16x16x32_bf16 v[56:59], v[186:189], v[194:197], v[16:19]
	v_mfma_f32_16x16x32_bf16 v[16:19], v[146:149], v[198:201], 0
	v_mfma_f32_16x16x32_bf16 v[44:47], v[150:153], v[202:205], v[16:19]
	v_mfma_f32_16x16x32_bf16 v[16:19], v[182:185], v[198:201], 0
	v_mfma_f32_16x16x32_bf16 v[40:43], v[186:189], v[202:205], v[16:19]
	v_mfma_f32_16x16x32_bf16 v[16:19], v[146:149], v[222:225], 0
	v_mfma_f32_16x16x32_bf16 v[28:31], v[150:153], v[226:229], v[16:19]
	v_mfma_f32_16x16x32_bf16 v[16:19], v[182:185], v[222:225], 0
	v_mfma_f32_16x16x32_bf16 v[12:15], v[146:149], v[230:233], 0
	v_mfma_f32_16x16x32_bf16 v[8:11], v[182:185], v[230:233], 0
	v_mfma_f32_16x16x32_bf16 v[24:27], v[186:189], v[226:229], v[16:19]
	v_mfma_f32_16x16x32_bf16 v[12:15], v[150:153], v[234:237], v[12:15]
	v_mfma_f32_16x16x32_bf16 v[8:11], v[186:189], v[234:237], v[8:11]
	s_setprio 0
	s_barrier
	s_add_i32 s33, 0, 0x1c000
	ds_read_b128 v[16:19], v253 offset:32768
	ds_read_b128 v[20:23], v253 offset:33792
	ds_read_b128 v[138:141], v253 offset:34816
	ds_read_b128 v[142:145], v253 offset:35840
	ds_read_b128 v[146:149], v253 offset:49152
	ds_read_b128 v[150:153], v253 offset:50176
	ds_read_b128 v[182:185], v253 offset:51200
	ds_read_b128 v[186:189], v253 offset:52224
	s_add_u32 s14, s14, 0x40000
	s_addc_u32 s15, s15, 0
	s_mov_b32 m0, s92
	ds_read_b128 v[190:193], v221 offset:32768
	ds_read_b128 v[194:197], v221 offset:33792
	ds_read_b128 v[198:201], v221 offset:34816
	ds_read_b128 v[202:205], v221 offset:35840
	ds_read_b128 v[222:225], v221 offset:36864
	ds_read_b128 v[226:229], v221 offset:37888
	ds_read_b128 v[230:233], v221 offset:38912
	ds_read_b128 v[234:237], v221 offset:39936
	global_load_lds_dwordx4 v154, s[14:15]
	s_mov_b32 m0, s93
	s_nop 0
	global_load_lds_dwordx4 v158, s[14:15]
	s_waitcnt vmcnt(8)
	s_waitcnt lgkmcnt(0)
	s_barrier
	s_setprio 1
	s_waitcnt lgkmcnt(0)
	v_mfma_f32_16x16x32_bf16 v[134:137], v[16:19], v[190:193], v[134:137]
	v_mfma_f32_16x16x32_bf16 v[130:133], v[138:141], v[190:193], v[130:133]
	v_mfma_f32_16x16x32_bf16 v[118:121], v[16:19], v[198:201], v[118:121]
	v_mfma_f32_16x16x32_bf16 v[114:117], v[138:141], v[198:201], v[114:117]
	v_mfma_f32_16x16x32_bf16 v[102:105], v[16:19], v[222:225], v[102:105]
	v_mfma_f32_16x16x32_bf16 v[98:101], v[138:141], v[222:225], v[98:101]
	v_mfma_f32_16x16x32_bf16 v[84:87], v[16:19], v[230:233], v[84:87]
	v_mfma_f32_16x16x32_bf16 v[80:83], v[138:141], v[230:233], v[80:83]
	v_mfma_f32_16x16x32_bf16 v[134:137], v[20:23], v[194:197], v[134:137]
	v_mfma_f32_16x16x32_bf16 v[130:133], v[142:145], v[194:197], v[130:133]
	v_mfma_f32_16x16x32_bf16 v[118:121], v[20:23], v[202:205], v[118:121]
	v_mfma_f32_16x16x32_bf16 v[114:117], v[142:145], v[202:205], v[114:117]
	v_mfma_f32_16x16x32_bf16 v[102:105], v[20:23], v[226:229], v[102:105]
	v_mfma_f32_16x16x32_bf16 v[98:101], v[142:145], v[226:229], v[98:101]
	v_mfma_f32_16x16x32_bf16 v[84:87], v[20:23], v[234:237], v[84:87]
	v_mfma_f32_16x16x32_bf16 v[80:83], v[142:145], v[234:237], v[80:83]
	s_setprio 0
	s_setprio 1
	v_mfma_f32_16x16x32_bf16 v[126:129], v[146:149], v[190:193], v[126:129]
	v_mfma_f32_16x16x32_bf16 v[122:125], v[182:185], v[190:193], v[122:125]
	v_mfma_f32_16x16x32_bf16 v[110:113], v[146:149], v[198:201], v[110:113]
	v_mfma_f32_16x16x32_bf16 v[106:109], v[182:185], v[198:201], v[106:109]
	v_mfma_f32_16x16x32_bf16 v[92:95], v[146:149], v[222:225], v[92:95]
	v_mfma_f32_16x16x32_bf16 v[88:91], v[182:185], v[222:225], v[88:91]
	v_mfma_f32_16x16x32_bf16 v[76:79], v[146:149], v[230:233], v[76:79]
	v_mfma_f32_16x16x32_bf16 v[72:75], v[182:185], v[230:233], v[72:75]
	v_mfma_f32_16x16x32_bf16 v[126:129], v[150:153], v[194:197], v[126:129]
	v_mfma_f32_16x16x32_bf16 v[122:125], v[186:189], v[194:197], v[122:125]
	v_mfma_f32_16x16x32_bf16 v[110:113], v[150:153], v[202:205], v[110:113]
	v_mfma_f32_16x16x32_bf16 v[106:109], v[186:189], v[202:205], v[106:109]
	v_mfma_f32_16x16x32_bf16 v[92:95], v[150:153], v[226:229], v[92:95]
	v_mfma_f32_16x16x32_bf16 v[88:91], v[186:189], v[226:229], v[88:91]
	v_mfma_f32_16x16x32_bf16 v[76:79], v[150:153], v[234:237], v[76:79]
	v_mfma_f32_16x16x32_bf16 v[72:75], v[186:189], v[234:237], v[72:75]
	s_setprio 0
	s_barrier
	s_add_i32 s14, s67, s78
	s_add_i32 m0, s14, 0xffffff80
	ds_read_b128 v[190:193], v221 offset:49152
	ds_read_b128 v[194:197], v221 offset:50176
	ds_read_b128 v[198:201], v221 offset:51200
	ds_read_b128 v[202:205], v221 offset:52224
	ds_read_b128 v[222:225], v221 offset:53248
	ds_read_b128 v[226:229], v221 offset:54272
	ds_read_b128 v[230:233], v221 offset:55296
	ds_read_b128 v[234:237], v221 offset:56320
	global_load_lds_dwordx4 v156, s[12:13] offset:128
	s_add_i32 m0, s14, 0x1f80
	s_add_i32 s14, s33, s78
	global_load_lds_dwordx4 v160, s[12:13] offset:128
	s_add_u32 s12, s12, 0x10080
	s_addc_u32 s13, s13, 0
	s_mov_b32 m0, s14
	s_nop 0
	global_load_lds_dwordx4 v156, s[12:13]
	s_add_i32 m0, s14, 0x2000
	s_nop 0
	global_load_lds_dwordx4 v160, s[12:13]
	s_add_i32 m0, s21, 0xffffff80
	s_nop 0
	global_load_lds_dwordx4 v154, s[42:43] offset:128
	s_add_i32 m0, s61, 0xffffff80
	s_nop 0
	global_load_lds_dwordx4 v158, s[42:43] offset:128
	s_waitcnt vmcnt(8)
	s_waitcnt lgkmcnt(0)
	s_barrier
	s_setprio 1
	s_waitcnt lgkmcnt(0)
	v_mfma_f32_16x16x32_bf16 v[68:71], v[16:19], v[190:193], v[68:71]
	v_mfma_f32_16x16x32_bf16 v[52:55], v[16:19], v[198:201], v[52:55]
	v_mfma_f32_16x16x32_bf16 v[36:39], v[16:19], v[222:225], v[36:39]
	v_mfma_f32_16x16x32_bf16 v[0:3], v[16:19], v[230:233], v[0:3]
	v_mfma_f32_16x16x32_bf16 v[68:71], v[20:23], v[194:197], v[68:71]
	v_mfma_f32_16x16x32_bf16 v[64:67], v[138:141], v[190:193], v[64:67]
	v_mfma_f32_16x16x32_bf16 v[52:55], v[20:23], v[202:205], v[52:55]
	v_mfma_f32_16x16x32_bf16 v[48:51], v[138:141], v[198:201], v[48:51]
	v_mfma_f32_16x16x32_bf16 v[36:39], v[20:23], v[226:229], v[36:39]
	v_mfma_f32_16x16x32_bf16 v[32:35], v[138:141], v[222:225], v[32:35]
	v_mfma_f32_16x16x32_bf16 v[20:23], v[20:23], v[234:237], v[0:3]
	v_mfma_f32_16x16x32_bf16 v[0:3], v[138:141], v[230:233], v[4:7]
	v_mfma_f32_16x16x32_bf16 v[64:67], v[142:145], v[194:197], v[64:67]
	v_mfma_f32_16x16x32_bf16 v[48:51], v[142:145], v[202:205], v[48:51]
	v_mfma_f32_16x16x32_bf16 v[32:35], v[142:145], v[226:229], v[32:35]
	v_mfma_f32_16x16x32_bf16 v[16:19], v[142:145], v[234:237], v[0:3]
	s_setprio 0
	s_setprio 1
	v_mfma_f32_16x16x32_bf16 v[0:3], v[146:149], v[190:193], v[60:63]
	v_mfma_f32_16x16x32_bf16 v[60:63], v[150:153], v[194:197], v[0:3]
	v_mfma_f32_16x16x32_bf16 v[0:3], v[182:185], v[190:193], v[56:59]
	v_mfma_f32_16x16x32_bf16 v[56:59], v[186:189], v[194:197], v[0:3]
	v_mfma_f32_16x16x32_bf16 v[0:3], v[146:149], v[198:201], v[44:47]
	v_mfma_f32_16x16x32_bf16 v[44:47], v[150:153], v[202:205], v[0:3]
	v_mfma_f32_16x16x32_bf16 v[0:3], v[182:185], v[198:201], v[40:43]
	v_mfma_f32_16x16x32_bf16 v[40:43], v[186:189], v[202:205], v[0:3]
	v_mfma_f32_16x16x32_bf16 v[0:3], v[146:149], v[222:225], v[28:31]
	v_mfma_f32_16x16x32_bf16 v[28:31], v[150:153], v[226:229], v[0:3]
	v_mfma_f32_16x16x32_bf16 v[0:3], v[182:185], v[222:225], v[24:27]
	v_mfma_f32_16x16x32_bf16 v[24:27], v[186:189], v[226:229], v[0:3]
	v_mfma_f32_16x16x32_bf16 v[0:3], v[146:149], v[230:233], v[12:15]
	v_mfma_f32_16x16x32_bf16 v[12:15], v[150:153], v[234:237], v[0:3]
	v_mfma_f32_16x16x32_bf16 v[0:3], v[182:185], v[230:233], v[8:11]
	v_mfma_f32_16x16x32_bf16 v[8:11], v[186:189], v[234:237], v[0:3]
	s_setprio 0
	s_barrier
	s_add_i32 s27, s27, 2
	s_add_u32 s4, s4, 0x100
	s_addc_u32 s5, s5, 0
	s_add_u32 s19, s19, 0x100
	s_addc_u32 s26, s26, 0
	.p2align 6
.LBB0_750:
	s_add_u32 s12, s4, 0xfffc0080
	s_addc_u32 s13, s5, -1
	s_add_i32 s33, 0, 0x10000
	s_cmp_eq_u32 s27, 12
	s_cselect_b32 s15, s3, s13
	s_cselect_b32 s14, s16, s12
	s_cselect_b32 s13, s17, s26
	s_cselect_b32 s12, s18, s19
	s_add_i32 s35, 0, 0x14000
	ds_read_b128 v[0:3], v253
	ds_read_b128 v[4:7], v253 offset:1024
	ds_read_b128 v[138:141], v253 offset:2048
	ds_read_b128 v[142:145], v253 offset:3072
	ds_read_b128 v[146:149], v253 offset:16384
	ds_read_b128 v[150:153], v253 offset:17408
	ds_read_b128 v[182:185], v253 offset:18432
	ds_read_b128 v[186:189], v253 offset:19456
	s_add_i32 m0, s79, 0xc000
	ds_read_b128 v[190:193], v221
	ds_read_b128 v[194:197], v221 offset:1024
	ds_read_b128 v[198:201], v221 offset:2048
	ds_read_b128 v[202:205], v221 offset:3072
	ds_read_b128 v[222:225], v221 offset:4096
	ds_read_b128 v[226:229], v221 offset:5120
	ds_read_b128 v[230:233], v221 offset:6144
	ds_read_b128 v[234:237], v221 offset:7168
	global_load_lds_dwordx4 v168, s[4:5]
	s_add_i32 m0, s79, 0xe000
	s_nop 0
	global_load_lds_dwordx4 v170, s[4:5]
	s_waitcnt vmcnt(8)
	s_waitcnt lgkmcnt(0)
	s_barrier
	s_setprio 1
	s_waitcnt lgkmcnt(0)
	v_mfma_f32_16x16x32_bf16 v[134:137], v[0:3], v[190:193], v[134:137]
	v_mfma_f32_16x16x32_bf16 v[130:133], v[138:141], v[190:193], v[130:133]
	v_mfma_f32_16x16x32_bf16 v[118:121], v[0:3], v[198:201], v[118:121]
	v_mfma_f32_16x16x32_bf16 v[114:117], v[138:141], v[198:201], v[114:117]
	v_mfma_f32_16x16x32_bf16 v[102:105], v[0:3], v[222:225], v[102:105]
	v_mfma_f32_16x16x32_bf16 v[98:101], v[138:141], v[222:225], v[98:101]
	v_mfma_f32_16x16x32_bf16 v[84:87], v[0:3], v[230:233], v[84:87]
	v_mfma_f32_16x16x32_bf16 v[80:83], v[138:141], v[230:233], v[80:83]
	v_mfma_f32_16x16x32_bf16 v[134:137], v[4:7], v[194:197], v[134:137]
	v_mfma_f32_16x16x32_bf16 v[130:133], v[142:145], v[194:197], v[130:133]
	v_mfma_f32_16x16x32_bf16 v[118:121], v[4:7], v[202:205], v[118:121]
	v_mfma_f32_16x16x32_bf16 v[114:117], v[142:145], v[202:205], v[114:117]
	v_mfma_f32_16x16x32_bf16 v[102:105], v[4:7], v[226:229], v[102:105]
	v_mfma_f32_16x16x32_bf16 v[98:101], v[142:145], v[226:229], v[98:101]
	v_mfma_f32_16x16x32_bf16 v[84:87], v[4:7], v[234:237], v[84:87]
	v_mfma_f32_16x16x32_bf16 v[80:83], v[142:145], v[234:237], v[80:83]
	s_setprio 0
	s_setprio 1
	v_mfma_f32_16x16x32_bf16 v[126:129], v[146:149], v[190:193], v[126:129]
	v_mfma_f32_16x16x32_bf16 v[122:125], v[182:185], v[190:193], v[122:125]
	v_mfma_f32_16x16x32_bf16 v[110:113], v[146:149], v[198:201], v[110:113]
	v_mfma_f32_16x16x32_bf16 v[106:109], v[182:185], v[198:201], v[106:109]
	v_mfma_f32_16x16x32_bf16 v[92:95], v[146:149], v[222:225], v[92:95]
	v_mfma_f32_16x16x32_bf16 v[88:91], v[182:185], v[222:225], v[88:91]
	v_mfma_f32_16x16x32_bf16 v[76:79], v[146:149], v[230:233], v[76:79]
	v_mfma_f32_16x16x32_bf16 v[72:75], v[182:185], v[230:233], v[72:75]
	v_mfma_f32_16x16x32_bf16 v[126:129], v[150:153], v[194:197], v[126:129]
	v_mfma_f32_16x16x32_bf16 v[122:125], v[186:189], v[194:197], v[122:125]
	v_mfma_f32_16x16x32_bf16 v[110:113], v[150:153], v[202:205], v[110:113]
	v_mfma_f32_16x16x32_bf16 v[106:109], v[186:189], v[202:205], v[106:109]
	v_mfma_f32_16x16x32_bf16 v[92:95], v[150:153], v[226:229], v[92:95]
	v_mfma_f32_16x16x32_bf16 v[88:91], v[186:189], v[226:229], v[88:91]
	v_mfma_f32_16x16x32_bf16 v[76:79], v[150:153], v[234:237], v[76:79]
	v_mfma_f32_16x16x32_bf16 v[72:75], v[186:189], v[234:237], v[72:75]
	s_setprio 0
	s_barrier
	s_add_i32 s33, s33, s78
	s_mov_b32 m0, s33
	ds_read_b128 v[190:193], v221 offset:16384
	ds_read_b128 v[194:197], v221 offset:17408
	ds_read_b128 v[198:201], v221 offset:18432
	ds_read_b128 v[202:205], v221 offset:19456
	ds_read_b128 v[222:225], v221 offset:20480
	ds_read_b128 v[226:229], v221 offset:21504
	ds_read_b128 v[230:233], v221 offset:22528
	ds_read_b128 v[234:237], v221 offset:23552
	global_load_lds_dwordx4 v156, s[12:13]
	s_add_i32 m0, s33, 0x2000
	s_add_u32 s42, s12, 0x10000
	s_addc_u32 s43, s13, 0
	s_add_i32 s33, s35, s78
	global_load_lds_dwordx4 v160, s[12:13]
	s_mov_b32 m0, s33
	s_nop 0
	global_load_lds_dwordx4 v156, s[42:43]
	s_add_i32 m0, s33, 0x2000
	s_nop 0
	global_load_lds_dwordx4 v160, s[42:43]
	s_mov_b64 s[42:43], s[14:15]
	s_mov_b32 m0, s79
	s_nop 0
	global_load_lds_dwordx4 v154, s[14:15]
	s_mov_b32 m0, s81
	s_nop 0
	global_load_lds_dwordx4 v158, s[14:15]
	s_waitcnt vmcnt(8)
	s_waitcnt lgkmcnt(0)
	s_barrier
	s_setprio 1
	s_waitcnt lgkmcnt(0)
	v_mfma_f32_16x16x32_bf16 v[68:71], v[0:3], v[190:193], v[68:71]
	v_mfma_f32_16x16x32_bf16 v[64:67], v[138:141], v[190:193], v[64:67]
	v_mfma_f32_16x16x32_bf16 v[52:55], v[0:3], v[198:201], v[52:55]
	v_mfma_f32_16x16x32_bf16 v[48:51], v[138:141], v[198:201], v[48:51]
	v_mfma_f32_16x16x32_bf16 v[36:39], v[0:3], v[222:225], v[36:39]
	v_mfma_f32_16x16x32_bf16 v[32:35], v[138:141], v[222:225], v[32:35]
	v_mfma_f32_16x16x32_bf16 v[0:3], v[0:3], v[230:233], v[20:23]
	v_mfma_f32_16x16x32_bf16 v[68:71], v[4:7], v[194:197], v[68:71]
	v_mfma_f32_16x16x32_bf16 v[64:67], v[142:145], v[194:197], v[64:67]
	v_mfma_f32_16x16x32_bf16 v[52:55], v[4:7], v[202:205], v[52:55]
	v_mfma_f32_16x16x32_bf16 v[48:51], v[142:145], v[202:205], v[48:51]
	v_mfma_f32_16x16x32_bf16 v[36:39], v[4:7], v[226:229], v[36:39]
	v_mfma_f32_16x16x32_bf16 v[32:35], v[142:145], v[226:229], v[32:35]
	v_mfma_f32_16x16x32_bf16 v[0:3], v[4:7], v[234:237], v[0:3]
	v_mfma_f32_16x16x32_bf16 v[4:7], v[138:141], v[230:233], v[16:19]
	v_mfma_f32_16x16x32_bf16 v[4:7], v[142:145], v[234:237], v[4:7]
	s_setprio 0
	s_setprio 1
	v_mfma_f32_16x16x32_bf16 v[16:19], v[146:149], v[190:193], v[60:63]
	v_mfma_f32_16x16x32_bf16 v[60:63], v[150:153], v[194:197], v[16:19]
	v_mfma_f32_16x16x32_bf16 v[16:19], v[182:185], v[190:193], v[56:59]
	v_mfma_f32_16x16x32_bf16 v[56:59], v[186:189], v[194:197], v[16:19]
	v_mfma_f32_16x16x32_bf16 v[16:19], v[146:149], v[198:201], v[44:47]
	v_mfma_f32_16x16x32_bf16 v[44:47], v[150:153], v[202:205], v[16:19]
	v_mfma_f32_16x16x32_bf16 v[16:19], v[182:185], v[198:201], v[40:43]
	v_mfma_f32_16x16x32_bf16 v[40:43], v[186:189], v[202:205], v[16:19]
	v_mfma_f32_16x16x32_bf16 v[16:19], v[146:149], v[222:225], v[28:31]
	v_mfma_f32_16x16x32_bf16 v[28:31], v[150:153], v[226:229], v[16:19]
	v_mfma_f32_16x16x32_bf16 v[16:19], v[182:185], v[222:225], v[24:27]
	v_mfma_f32_16x16x32_bf16 v[12:15], v[146:149], v[230:233], v[12:15]
	v_mfma_f32_16x16x32_bf16 v[8:11], v[182:185], v[230:233], v[8:11]
	v_mfma_f32_16x16x32_bf16 v[24:27], v[186:189], v[226:229], v[16:19]
	v_mfma_f32_16x16x32_bf16 v[12:15], v[150:153], v[234:237], v[12:15]
	v_mfma_f32_16x16x32_bf16 v[8:11], v[186:189], v[234:237], v[8:11]
	s_setprio 0
	s_barrier
	s_add_i32 s33, 0, 0x1c000
	ds_read_b128 v[16:19], v253 offset:32768
	ds_read_b128 v[20:23], v253 offset:33792
	ds_read_b128 v[138:141], v253 offset:34816
	ds_read_b128 v[142:145], v253 offset:35840
	ds_read_b128 v[146:149], v253 offset:49152
	ds_read_b128 v[150:153], v253 offset:50176
	ds_read_b128 v[182:185], v253 offset:51200
	ds_read_b128 v[186:189], v253 offset:52224
	s_add_u32 s14, s14, 0x40000
	s_addc_u32 s15, s15, 0
	s_mov_b32 m0, s92
	ds_read_b128 v[190:193], v221 offset:32768
	ds_read_b128 v[194:197], v221 offset:33792
	ds_read_b128 v[198:201], v221 offset:34816
	ds_read_b128 v[202:205], v221 offset:35840
	ds_read_b128 v[222:225], v221 offset:36864
	ds_read_b128 v[226:229], v221 offset:37888
	ds_read_b128 v[230:233], v221 offset:38912
	ds_read_b128 v[234:237], v221 offset:39936
	global_load_lds_dwordx4 v154, s[14:15]
	s_mov_b32 m0, s93
	s_nop 0
	global_load_lds_dwordx4 v158, s[14:15]
	s_waitcnt vmcnt(8)
	s_waitcnt lgkmcnt(0)
	s_barrier
	s_setprio 1
	s_waitcnt lgkmcnt(0)
	v_mfma_f32_16x16x32_bf16 v[134:137], v[16:19], v[190:193], v[134:137]
	v_mfma_f32_16x16x32_bf16 v[130:133], v[138:141], v[190:193], v[130:133]
	v_mfma_f32_16x16x32_bf16 v[118:121], v[16:19], v[198:201], v[118:121]
	v_mfma_f32_16x16x32_bf16 v[114:117], v[138:141], v[198:201], v[114:117]
	v_mfma_f32_16x16x32_bf16 v[102:105], v[16:19], v[222:225], v[102:105]
	v_mfma_f32_16x16x32_bf16 v[98:101], v[138:141], v[222:225], v[98:101]
	v_mfma_f32_16x16x32_bf16 v[84:87], v[16:19], v[230:233], v[84:87]
	v_mfma_f32_16x16x32_bf16 v[80:83], v[138:141], v[230:233], v[80:83]
	v_mfma_f32_16x16x32_bf16 v[134:137], v[20:23], v[194:197], v[134:137]
	v_mfma_f32_16x16x32_bf16 v[130:133], v[142:145], v[194:197], v[130:133]
	v_mfma_f32_16x16x32_bf16 v[118:121], v[20:23], v[202:205], v[118:121]
	v_mfma_f32_16x16x32_bf16 v[114:117], v[142:145], v[202:205], v[114:117]
	v_mfma_f32_16x16x32_bf16 v[102:105], v[20:23], v[226:229], v[102:105]
	v_mfma_f32_16x16x32_bf16 v[98:101], v[142:145], v[226:229], v[98:101]
	v_mfma_f32_16x16x32_bf16 v[84:87], v[20:23], v[234:237], v[84:87]
	v_mfma_f32_16x16x32_bf16 v[80:83], v[142:145], v[234:237], v[80:83]
	s_setprio 0
	s_setprio 1
	v_mfma_f32_16x16x32_bf16 v[126:129], v[146:149], v[190:193], v[126:129]
	v_mfma_f32_16x16x32_bf16 v[122:125], v[182:185], v[190:193], v[122:125]
	v_mfma_f32_16x16x32_bf16 v[110:113], v[146:149], v[198:201], v[110:113]
	v_mfma_f32_16x16x32_bf16 v[106:109], v[182:185], v[198:201], v[106:109]
	v_mfma_f32_16x16x32_bf16 v[92:95], v[146:149], v[222:225], v[92:95]
	v_mfma_f32_16x16x32_bf16 v[88:91], v[182:185], v[222:225], v[88:91]
	v_mfma_f32_16x16x32_bf16 v[76:79], v[146:149], v[230:233], v[76:79]
	v_mfma_f32_16x16x32_bf16 v[72:75], v[182:185], v[230:233], v[72:75]
	v_mfma_f32_16x16x32_bf16 v[126:129], v[150:153], v[194:197], v[126:129]
	v_mfma_f32_16x16x32_bf16 v[122:125], v[186:189], v[194:197], v[122:125]
	v_mfma_f32_16x16x32_bf16 v[110:113], v[150:153], v[202:205], v[110:113]
	v_mfma_f32_16x16x32_bf16 v[106:109], v[186:189], v[202:205], v[106:109]
	v_mfma_f32_16x16x32_bf16 v[92:95], v[150:153], v[226:229], v[92:95]
	v_mfma_f32_16x16x32_bf16 v[88:91], v[186:189], v[226:229], v[88:91]
	v_mfma_f32_16x16x32_bf16 v[76:79], v[150:153], v[234:237], v[76:79]
	v_mfma_f32_16x16x32_bf16 v[72:75], v[186:189], v[234:237], v[72:75]
	s_setprio 0
	s_barrier
	s_add_i32 s14, s67, s78
	s_add_i32 m0, s14, 0xffffff80
	ds_read_b128 v[190:193], v221 offset:49152
	ds_read_b128 v[194:197], v221 offset:50176
	ds_read_b128 v[198:201], v221 offset:51200
	ds_read_b128 v[202:205], v221 offset:52224
	ds_read_b128 v[222:225], v221 offset:53248
	ds_read_b128 v[226:229], v221 offset:54272
	ds_read_b128 v[230:233], v221 offset:55296
	ds_read_b128 v[234:237], v221 offset:56320
	global_load_lds_dwordx4 v156, s[12:13] offset:128
	s_add_i32 m0, s14, 0x1f80
	s_add_i32 s14, s33, s78
	global_load_lds_dwordx4 v160, s[12:13] offset:128
	s_add_u32 s12, s12, 0x10080
	s_addc_u32 s13, s13, 0
	s_mov_b32 m0, s14
	s_nop 0
	global_load_lds_dwordx4 v156, s[12:13]
	s_add_i32 m0, s14, 0x2000
	s_nop 0
	global_load_lds_dwordx4 v160, s[12:13]
	s_add_i32 m0, s21, 0xffffff80
	s_nop 0
	global_load_lds_dwordx4 v154, s[42:43] offset:128
	s_add_i32 m0, s61, 0xffffff80
	s_nop 0
	global_load_lds_dwordx4 v158, s[42:43] offset:128
	s_waitcnt vmcnt(8)
	s_waitcnt lgkmcnt(0)
	s_barrier
	s_setprio 1
	s_waitcnt lgkmcnt(0)
	v_mfma_f32_16x16x32_bf16 v[68:71], v[16:19], v[190:193], v[68:71]
	v_mfma_f32_16x16x32_bf16 v[52:55], v[16:19], v[198:201], v[52:55]
	v_mfma_f32_16x16x32_bf16 v[36:39], v[16:19], v[222:225], v[36:39]
	v_mfma_f32_16x16x32_bf16 v[0:3], v[16:19], v[230:233], v[0:3]
	v_mfma_f32_16x16x32_bf16 v[68:71], v[20:23], v[194:197], v[68:71]
	v_mfma_f32_16x16x32_bf16 v[64:67], v[138:141], v[190:193], v[64:67]
	v_mfma_f32_16x16x32_bf16 v[52:55], v[20:23], v[202:205], v[52:55]
	v_mfma_f32_16x16x32_bf16 v[48:51], v[138:141], v[198:201], v[48:51]
	v_mfma_f32_16x16x32_bf16 v[36:39], v[20:23], v[226:229], v[36:39]
	v_mfma_f32_16x16x32_bf16 v[32:35], v[138:141], v[222:225], v[32:35]
	v_mfma_f32_16x16x32_bf16 v[20:23], v[20:23], v[234:237], v[0:3]
	v_mfma_f32_16x16x32_bf16 v[0:3], v[138:141], v[230:233], v[4:7]
	v_mfma_f32_16x16x32_bf16 v[64:67], v[142:145], v[194:197], v[64:67]
	v_mfma_f32_16x16x32_bf16 v[48:51], v[142:145], v[202:205], v[48:51]
	v_mfma_f32_16x16x32_bf16 v[32:35], v[142:145], v[226:229], v[32:35]
	v_mfma_f32_16x16x32_bf16 v[16:19], v[142:145], v[234:237], v[0:3]
	s_setprio 0
	s_setprio 1
	v_mfma_f32_16x16x32_bf16 v[0:3], v[146:149], v[190:193], v[60:63]
	v_mfma_f32_16x16x32_bf16 v[60:63], v[150:153], v[194:197], v[0:3]
	v_mfma_f32_16x16x32_bf16 v[0:3], v[182:185], v[190:193], v[56:59]
	v_mfma_f32_16x16x32_bf16 v[56:59], v[186:189], v[194:197], v[0:3]
	v_mfma_f32_16x16x32_bf16 v[0:3], v[146:149], v[198:201], v[44:47]
	v_mfma_f32_16x16x32_bf16 v[44:47], v[150:153], v[202:205], v[0:3]
	v_mfma_f32_16x16x32_bf16 v[0:3], v[182:185], v[198:201], v[40:43]
	v_mfma_f32_16x16x32_bf16 v[40:43], v[186:189], v[202:205], v[0:3]
	v_mfma_f32_16x16x32_bf16 v[0:3], v[146:149], v[222:225], v[28:31]
	v_mfma_f32_16x16x32_bf16 v[28:31], v[150:153], v[226:229], v[0:3]
	v_mfma_f32_16x16x32_bf16 v[0:3], v[182:185], v[222:225], v[24:27]
	v_mfma_f32_16x16x32_bf16 v[24:27], v[186:189], v[226:229], v[0:3]
	v_mfma_f32_16x16x32_bf16 v[0:3], v[146:149], v[230:233], v[12:15]
	v_mfma_f32_16x16x32_bf16 v[12:15], v[150:153], v[234:237], v[0:3]
	v_mfma_f32_16x16x32_bf16 v[0:3], v[182:185], v[230:233], v[8:11]
	v_mfma_f32_16x16x32_bf16 v[8:11], v[186:189], v[234:237], v[0:3]
	s_setprio 0
	s_barrier
	s_add_i32 s27, s27, 2
	s_add_u32 s4, s4, 0x100
	s_addc_u32 s5, s5, 0
	s_add_u32 s19, s19, 0x100
	s_addc_u32 s26, s26, 0
	s_cmp_gt_u32 s27, 13
	s_cbranch_scc0 .LBB0_750
	v_readlane_b32 s4, v252, 30
	v_readlane_b32 s5, v252, 31
	s_and_b64 vcc, exec, s[4:5]
	s_cbranch_vccz .LBB0_753
	s_barrier

	.amdhsa_kernel _Z6mk_fwd4Args
		.amdhsa_group_segment_fixed_size 0
		.amdhsa_private_segment_fixed_size 0
		.amdhsa_kernarg_size 424
		.amdhsa_user_sgpr_count 2
		.amdhsa_user_sgpr_dispatch_ptr 0
		.amdhsa_user_sgpr_queue_ptr 0
		.amdhsa_user_sgpr_kernarg_segment_ptr 1
		.amdhsa_user_sgpr_dispatch_id 0
		.amdhsa_user_sgpr_kernarg_preload_length 0
		.amdhsa_user_sgpr_kernarg_preload_offset 0
		.amdhsa_user_sgpr_private_segment_size 0
		.amdhsa_uses_dynamic_stack 0
		.amdhsa_enable_private_segment 0
		.amdhsa_system_sgpr_workgroup_id_x 1
		.amdhsa_system_sgpr_workgroup_id_y 0
		.amdhsa_system_sgpr_workgroup_id_z 0
		.amdhsa_system_sgpr_workgroup_info 0
		.amdhsa_system_vgpr_workitem_id 2
		.amdhsa_next_free_vgpr 254
		.amdhsa_next_free_sgpr 102
		.amdhsa_accum_offset 256
		.amdhsa_reserve_vcc 1
		.amdhsa_float_round_mode_32 0
		.amdhsa_float_round_mode_16_64 0
		.amdhsa_float_denorm_mode_32 3
		.amdhsa_float_denorm_mode_16_64 3
		.amdhsa_dx10_clamp 1
		.amdhsa_ieee_mode 1
		.amdhsa_fp16_overflow 0
		.amdhsa_tg_split 0
		.amdhsa_exception_fp_ieee_invalid_op 0
		.amdhsa_exception_fp_denorm_src 0
		.amdhsa_exception_fp_ieee_div_zero 0
		.amdhsa_exception_fp_ieee_overflow 0
		.amdhsa_exception_fp_ieee_underflow 0
		.amdhsa_exception_fp_ieee_inexact 0
		.amdhsa_exception_int_div_zero 0
	.end_amdhsa_kernel

amdhsa.kernels:
  - .agpr_count:     0
    .args:
      - .offset:         0
        .size:           168
        .value_kind:     by_value
      - .offset:         168
        .size:           4
        .value_kind:     hidden_block_count_x
      - .offset:         172
        .size:           4
        .value_kind:     hidden_block_count_y
      - .offset:         176
        .size:           4
        .value_kind:     hidden_block_count_z
      - .offset:         180
        .size:           2
        .value_kind:     hidden_group_size_x
      - .offset:         182
        .size:           2
        .value_kind:     hidden_group_size_y
      - .offset:         184
        .size:           2
        .value_kind:     hidden_group_size_z
      - .offset:         186
        .size:           2
        .value_kind:     hidden_remainder_x
      - .offset:         188
        .size:           2
        .value_kind:     hidden_remainder_y
      - .offset:         190
        .size:           2
        .value_kind:     hidden_remainder_z
      - .offset:         208
        .size:           8
        .value_kind:     hidden_global_offset_x
      - .offset:         216
        .size:           8
        .value_kind:     hidden_global_offset_y
      - .offset:         224
        .size:           8
        .value_kind:     hidden_global_offset_z
      - .offset:         232
        .size:           2
        .value_kind:     hidden_grid_dims
      - .offset:         256
        .size:           8
        .value_kind:     hidden_multigrid_sync_arg
      - .offset:         288
        .size:           4
        .value_kind:     hidden_dynamic_lds_size
    .group_segment_fixed_size: 0
    .kernarg_segment_align: 8
    .kernarg_segment_size: 424
    .language:       OpenCL C
    .language_version:
      - 2
      - 0
    .max_flat_workgroup_size: 512
    .name:           _Z6mk_fwd4Args
    .private_segment_fixed_size: 0
    .sgpr_count:     108
    .sgpr_spill_count: 57
    .symbol:         _Z6mk_fwd4Args.kd
    .uniform_work_group_size: 1
    .uses_dynamic_stack: false
    .vgpr_count:     254
    .vgpr_spill_count: 0
    .wavefront_size: 64
